# GEMM prologue/epilogue trims (loads before accumulator clear, no s_nop before LDS-DMA, packed square, counted read-back waits) + scan after MLA for second workgroup
# speedup vs baseline: 1.0037x; 1.0037x over previous
.Lg2_ff2_tile:
	s_lshl_b32 s0, s64, 3
	s_add_i32 s38, s0, s68
	s_mov_b32 s69, s42
	s_mov_b32 s65, s43
	s_lshl_b32 s0, s38, 7
	s_mul_i32 s2, s69, 0x2000
	s_mul_hi_u32 s3, s69, 0x2000
	s_add_u32 s56, s26, s2
	s_addc_u32 s57, s27, s3
	s_add_u32 s56, s56, 0x0
	s_addc_u32 s57, s57, 0
	s_mul_i32 s2, s0, 0x2000
	s_mul_hi_u32 s3, s0, 0x2000
	s_add_u32 s58, s26, s2
	s_addc_u32 s59, s27, s3
	s_add_u32 s58, s58, 0x10740000
	s_addc_u32 s59, s59, 0
	s_mul_i32 s2, s69, 0x800
	s_mul_hi_u32 s3, s69, 0x800
	s_lshl_b32 s0, s0, 1
	s_add_u32 s2, s2, s0
	s_addc_u32 s3, s3, 0
	s_add_u32 s60, s26, s2
	s_addc_u32 s61, s27, s3
	s_add_u32 s60, s60, 0x11140000
	s_addc_u32 s61, s61, 0
	s_cmp_eq_u32 s65, 0
	s_cbranch_scc1 .Lg2_ff2_k16
	s_add_u32 m0, s62, 0x0
	s_add_u32 s4, s56, 0x0
	s_addc_u32 s5, s57, 0
	global_load_lds_dwordx4 v162, s[4:5]
	s_add_u32 m0, s62, 0x1000
	s_add_u32 s4, s56, 0x40000
	s_addc_u32 s5, s57, 0
	global_load_lds_dwordx4 v162, s[4:5]
	s_add_u32 m0, s62, 0x2000
	s_add_u32 s4, s56, 0x80000
	s_addc_u32 s5, s57, 0
	global_load_lds_dwordx4 v162, s[4:5]
	s_add_u32 m0, s62, 0x3000
	s_add_u32 s4, s56, 0xc0000
	s_addc_u32 s5, s57, 0
	global_load_lds_dwordx4 v162, s[4:5]
	s_add_u32 m0, s62, 0x4000
	s_add_u32 s4, s56, 0x100000
	s_addc_u32 s5, s57, 0
	global_load_lds_dwordx4 v162, s[4:5]
	s_add_u32 m0, s62, 0x5000
	s_add_u32 s4, s56, 0x140000
	s_addc_u32 s5, s57, 0
	global_load_lds_dwordx4 v162, s[4:5]
	s_add_u32 m0, s62, 0x6000
	s_add_u32 s4, s56, 0x180000
	s_addc_u32 s5, s57, 0
	global_load_lds_dwordx4 v162, s[4:5]
	s_add_u32 m0, s62, 0x7000
	s_add_u32 s4, s56, 0x1c0000
	s_addc_u32 s5, s57, 0
	global_load_lds_dwordx4 v162, s[4:5]
	s_cmp_gt_u32 s70, 1
	s_cbranch_scc1 .Lg2_ff2_nodma_0
	s_add_u32 m0, s62, 0x8000
	s_add_u32 s4, s56, 0x200000
	s_addc_u32 s5, s57, 0
	global_load_lds_dwordx4 v162, s[4:5]

.Lg2_ff2_loop17:
	s_waitcnt vmcnt(0)
	s_barrier
	s_add_u32 s56, s56, 0x80
	s_addc_u32 s57, s57, 0
	s_add_u32 s58, s58, 0x800
	s_addc_u32 s59, s59, 0
	s_add_u32 m0, s62, 0x8800
	s_add_u32 s4, s56, 0x0
	s_addc_u32 s5, s57, 0
	global_load_lds_dwordx4 v162, s[4:5]
	s_add_u32 m0, s62, 0x9800
	s_add_u32 s4, s56, 0x40000
	s_addc_u32 s5, s57, 0
	global_load_lds_dwordx4 v162, s[4:5]
	s_add_u32 m0, s62, 0xa800
	s_add_u32 s4, s56, 0x80000
	s_addc_u32 s5, s57, 0
	global_load_lds_dwordx4 v162, s[4:5]
	s_add_u32 m0, s62, 0xb800
	s_add_u32 s4, s56, 0xc0000
	s_addc_u32 s5, s57, 0
	global_load_lds_dwordx4 v162, s[4:5]
	s_add_u32 m0, s62, 0xc800
	s_add_u32 s4, s56, 0x100000
	s_addc_u32 s5, s57, 0
	global_load_lds_dwordx4 v162, s[4:5]
	s_add_u32 m0, s62, 0xd800
	s_add_u32 s4, s56, 0x140000
	s_addc_u32 s5, s57, 0
	global_load_lds_dwordx4 v162, s[4:5]
	s_add_u32 m0, s62, 0xe800
	s_add_u32 s4, s56, 0x180000
	s_addc_u32 s5, s57, 0
	global_load_lds_dwordx4 v162, s[4:5]
	s_add_u32 m0, s62, 0xf800
	s_add_u32 s4, s56, 0x1c0000
	s_addc_u32 s5, s57, 0
	global_load_lds_dwordx4 v162, s[4:5]
	s_cmp_gt_u32 s70, 1
	s_cbranch_scc1 .Lg2_ff2_nodma_1
	s_add_u32 m0, s62, 0x10800
	s_add_u32 s4, s56, 0x200000
	s_addc_u32 s5, s57, 0
	global_load_lds_dwordx4 v162, s[4:5]
.Lg2_ff2_nodma_1:
	global_load_dwordx4 v[200:203], v160, s[58:59] offset:0
	global_load_dwordx4 v[204:207], v160, s[58:59] offset:1024
	global_load_dwordx4 v[208:211], v161, s[58:59] offset:0
	global_load_dwordx4 v[240:243], v161, s[58:59] offset:1024
	ds_read_b128 v[136:139], v156 offset:0
	ds_read_b128 v[140:143], v156 offset:2048
	ds_read_b128 v[144:147], v156 offset:4096
	ds_read_b128 v[148:151], v156 offset:6144
	ds_read_b128 v[164:167], v156 offset:8192
	ds_read_b128 v[168:171], v156 offset:10240
	ds_read_b128 v[172:175], v156 offset:12288
	ds_read_b128 v[176:179], v156 offset:14336
	s_waitcnt lgkmcnt(4)
	v_mfma_f32_16x16x32_bf16 v[0:3], v[184:187], v[136:139], v[0:3]
	v_mfma_f32_16x16x32_bf16 v[4:7], v[192:195], v[136:139], v[4:7]
	v_mfma_f32_16x16x32_bf16 v[8:11], v[184:187], v[140:143], v[8:11]
	v_mfma_f32_16x16x32_bf16 v[12:15], v[192:195], v[140:143], v[12:15]
	v_mfma_f32_16x16x32_bf16 v[16:19], v[184:187], v[144:147], v[16:19]
	v_mfma_f32_16x16x32_bf16 v[20:23], v[192:195], v[144:147], v[20:23]
	v_mfma_f32_16x16x32_bf16 v[24:27], v[184:187], v[148:151], v[24:27]
	v_mfma_f32_16x16x32_bf16 v[28:31], v[192:195], v[148:151], v[28:31]
	ds_read_b128 v[136:139], v156 offset:16384
	ds_read_b128 v[140:143], v156 offset:18432
	ds_read_b128 v[144:147], v156 offset:20480
	ds_read_b128 v[148:151], v156 offset:22528
	s_waitcnt lgkmcnt(4)
	v_mfma_f32_16x16x32_bf16 v[32:35], v[184:187], v[164:167], v[32:35]
	v_mfma_f32_16x16x32_bf16 v[36:39], v[192:195], v[164:167], v[36:39]
	v_mfma_f32_16x16x32_bf16 v[40:43], v[184:187], v[168:171], v[40:43]
	v_mfma_f32_16x16x32_bf16 v[44:47], v[192:195], v[168:171], v[44:47]
	v_mfma_f32_16x16x32_bf16 v[48:51], v[184:187], v[172:175], v[48:51]
	v_mfma_f32_16x16x32_bf16 v[52:55], v[192:195], v[172:175], v[52:55]
	v_mfma_f32_16x16x32_bf16 v[56:59], v[184:187], v[176:179], v[56:59]
	v_mfma_f32_16x16x32_bf16 v[60:63], v[192:195], v[176:179], v[60:63]
	ds_read_b128 v[164:167], v156 offset:24576
	ds_read_b128 v[168:171], v156 offset:26624
	ds_read_b128 v[172:175], v156 offset:28672
	ds_read_b128 v[176:179], v156 offset:30720
	ds_read_b128 v[180:183], v156 offset:32768
	s_waitcnt lgkmcnt(5)
	v_mfma_f32_16x16x32_bf16 v[64:67], v[184:187], v[136:139], v[64:67]
	v_mfma_f32_16x16x32_bf16 v[68:71], v[192:195], v[136:139], v[68:71]
	v_mfma_f32_16x16x32_bf16 v[72:75], v[184:187], v[140:143], v[72:75]
	v_mfma_f32_16x16x32_bf16 v[76:79], v[192:195], v[140:143], v[76:79]
	v_mfma_f32_16x16x32_bf16 v[80:83], v[184:187], v[144:147], v[80:83]
	v_mfma_f32_16x16x32_bf16 v[84:87], v[192:195], v[144:147], v[84:87]
	v_mfma_f32_16x16x32_bf16 v[88:91], v[184:187], v[148:151], v[88:91]
	v_mfma_f32_16x16x32_bf16 v[92:95], v[192:195], v[148:151], v[92:95]
	ds_read_b128 v[136:139], v157 offset:0
	ds_read_b128 v[140:143], v157 offset:2048
	ds_read_b128 v[144:147], v157 offset:4096
	ds_read_b128 v[148:151], v157 offset:6144
	s_waitcnt lgkmcnt(4)
	v_mfma_f32_16x16x32_bf16 v[96:99], v[184:187], v[164:167], v[96:99]
	v_mfma_f32_16x16x32_bf16 v[100:103], v[192:195], v[164:167], v[100:103]
	v_mfma_f32_16x16x32_bf16 v[104:107], v[184:187], v[168:171], v[104:107]
	v_mfma_f32_16x16x32_bf16 v[108:111], v[192:195], v[168:171], v[108:111]
	v_mfma_f32_16x16x32_bf16 v[112:115], v[184:187], v[172:175], v[112:115]
	v_mfma_f32_16x16x32_bf16 v[116:119], v[192:195], v[172:175], v[116:119]
	v_mfma_f32_16x16x32_bf16 v[120:123], v[184:187], v[176:179], v[120:123]
	v_mfma_f32_16x16x32_bf16 v[124:127], v[192:195], v[176:179], v[124:127]
	v_mfma_f32_16x16x32_bf16 v[128:131], v[184:187], v[180:183], v[128:131]
	v_mfma_f32_16x16x32_bf16 v[132:135], v[192:195], v[180:183], v[132:135]
	ds_read_b128 v[164:167], v157 offset:8192
	ds_read_b128 v[168:171], v157 offset:10240
	ds_read_b128 v[172:175], v157 offset:12288
	ds_read_b128 v[176:179], v157 offset:14336
	s_waitcnt lgkmcnt(4)
	v_mfma_f32_16x16x32_bf16 v[0:3], v[188:191], v[136:139], v[0:3]
	v_mfma_f32_16x16x32_bf16 v[4:7], v[196:199], v[136:139], v[4:7]
	v_mfma_f32_16x16x32_bf16 v[8:11], v[188:191], v[140:143], v[8:11]
	v_mfma_f32_16x16x32_bf16 v[12:15], v[196:199], v[140:143], v[12:15]
	v_mfma_f32_16x16x32_bf16 v[16:19], v[188:191], v[144:147], v[16:19]
	v_mfma_f32_16x16x32_bf16 v[20:23], v[196:199], v[144:147], v[20:23]
	v_mfma_f32_16x16x32_bf16 v[24:27], v[188:191], v[148:151], v[24:27]
	v_mfma_f32_16x16x32_bf16 v[28:31], v[196:199], v[148:151], v[28:31]
	ds_read_b128 v[136:139], v157 offset:16384
	ds_read_b128 v[140:143], v157 offset:18432
	ds_read_b128 v[144:147], v157 offset:20480
	ds_read_b128 v[148:151], v157 offset:22528
	s_waitcnt lgkmcnt(4)
	v_mfma_f32_16x16x32_bf16 v[32:35], v[188:191], v[164:167], v[32:35]
	v_mfma_f32_16x16x32_bf16 v[36:39], v[196:199], v[164:167], v[36:39]
	v_mfma_f32_16x16x32_bf16 v[40:43], v[188:191], v[168:171], v[40:43]
	v_mfma_f32_16x16x32_bf16 v[44:47], v[196:199], v[168:171], v[44:47]
	v_mfma_f32_16x16x32_bf16 v[48:51], v[188:191], v[172:175], v[48:51]
	v_mfma_f32_16x16x32_bf16 v[52:55], v[196:199], v[172:175], v[52:55]
	v_mfma_f32_16x16x32_bf16 v[56:59], v[188:191], v[176:179], v[56:59]
	v_mfma_f32_16x16x32_bf16 v[60:63], v[196:199], v[176:179], v[60:63]
	ds_read_b128 v[164:167], v157 offset:24576
	ds_read_b128 v[168:171], v157 offset:26624
	ds_read_b128 v[172:175], v157 offset:28672
	ds_read_b128 v[176:179], v157 offset:30720
	ds_read_b128 v[180:183], v157 offset:32768
	s_waitcnt lgkmcnt(5)
	v_mfma_f32_16x16x32_bf16 v[64:67], v[188:191], v[136:139], v[64:67]
	v_mfma_f32_16x16x32_bf16 v[68:71], v[196:199], v[136:139], v[68:71]
	v_mfma_f32_16x16x32_bf16 v[72:75], v[188:191], v[140:143], v[72:75]
	v_mfma_f32_16x16x32_bf16 v[76:79], v[196:199], v[140:143], v[76:79]
	v_mfma_f32_16x16x32_bf16 v[80:83], v[188:191], v[144:147], v[80:83]
	v_mfma_f32_16x16x32_bf16 v[84:87], v[196:199], v[144:147], v[84:87]
	v_mfma_f32_16x16x32_bf16 v[88:91], v[188:191], v[148:151], v[88:91]
	v_mfma_f32_16x16x32_bf16 v[92:95], v[196:199], v[148:151], v[92:95]
	s_waitcnt lgkmcnt(0)
	v_mfma_f32_16x16x32_bf16 v[96:99], v[188:191], v[164:167], v[96:99]
	v_mfma_f32_16x16x32_bf16 v[100:103], v[196:199], v[164:167], v[100:103]
	v_mfma_f32_16x16x32_bf16 v[104:107], v[188:191], v[168:171], v[104:107]
	v_mfma_f32_16x16x32_bf16 v[108:111], v[196:199], v[168:171], v[108:111]
	v_mfma_f32_16x16x32_bf16 v[112:115], v[188:191], v[172:175], v[112:115]
	v_mfma_f32_16x16x32_bf16 v[116:119], v[196:199], v[172:175], v[116:119]
	v_mfma_f32_16x16x32_bf16 v[120:123], v[188:191], v[176:179], v[120:123]
	v_mfma_f32_16x16x32_bf16 v[124:127], v[196:199], v[176:179], v[124:127]
	v_mfma_f32_16x16x32_bf16 v[128:131], v[188:191], v[180:183], v[128:131]
	v_mfma_f32_16x16x32_bf16 v[132:135], v[196:199], v[180:183], v[132:135]
	s_waitcnt vmcnt(0)
	s_barrier
	s_cmp_ge_u32 s63, 62
	s_cbranch_scc1 .Lg2_ff2_noissue17
	s_add_u32 s56, s56, 0x80
	s_addc_u32 s57, s57, 0
	s_add_u32 s58, s58, 0x800
	s_addc_u32 s59, s59, 0
	s_add_u32 m0, s62, 0x0
	s_add_u32 s4, s56, 0x0
	s_addc_u32 s5, s57, 0
	global_load_lds_dwordx4 v162, s[4:5]
	s_add_u32 m0, s62, 0x1000
	s_add_u32 s4, s56, 0x40000
	s_addc_u32 s5, s57, 0
	global_load_lds_dwordx4 v162, s[4:5]
	s_add_u32 m0, s62, 0x2000
	s_add_u32 s4, s56, 0x80000
	s_addc_u32 s5, s57, 0
	global_load_lds_dwordx4 v162, s[4:5]
	s_add_u32 m0, s62, 0x3000
	s_add_u32 s4, s56, 0xc0000
	s_addc_u32 s5, s57, 0
	global_load_lds_dwordx4 v162, s[4:5]
	s_add_u32 m0, s62, 0x4000
	s_add_u32 s4, s56, 0x100000
	s_addc_u32 s5, s57, 0
	global_load_lds_dwordx4 v162, s[4:5]
	s_add_u32 m0, s62, 0x5000
	s_add_u32 s4, s56, 0x140000
	s_addc_u32 s5, s57, 0
	global_load_lds_dwordx4 v162, s[4:5]
	s_add_u32 m0, s62, 0x6000
	s_add_u32 s4, s56, 0x180000
	s_addc_u32 s5, s57, 0
	global_load_lds_dwordx4 v162, s[4:5]
	s_add_u32 m0, s62, 0x7000
	s_add_u32 s4, s56, 0x1c0000
	s_addc_u32 s5, s57, 0
	global_load_lds_dwordx4 v162, s[4:5]
	s_cmp_gt_u32 s70, 1
	s_cbranch_scc1 .Lg2_ff2_nodma_2
	s_add_u32 m0, s62, 0x8000
	s_add_u32 s4, s56, 0x200000
	s_addc_u32 s5, s57, 0
	global_load_lds_dwordx4 v162, s[4:5]

.Lg2_ff2_k16:
	s_add_u32 m0, s62, 0x0
	s_add_u32 s4, s56, 0x0
	s_addc_u32 s5, s57, 0
	global_load_lds_dwordx4 v162, s[4:5]
	s_add_u32 m0, s62, 0x1000
	s_add_u32 s4, s56, 0x40000
	s_addc_u32 s5, s57, 0
	global_load_lds_dwordx4 v162, s[4:5]
	s_add_u32 m0, s62, 0x2000
	s_add_u32 s4, s56, 0x80000
	s_addc_u32 s5, s57, 0
	global_load_lds_dwordx4 v162, s[4:5]
	s_add_u32 m0, s62, 0x3000
	s_add_u32 s4, s56, 0xc0000
	s_addc_u32 s5, s57, 0
	global_load_lds_dwordx4 v162, s[4:5]
	s_add_u32 m0, s62, 0x4000
	s_add_u32 s4, s56, 0x100000
	s_addc_u32 s5, s57, 0
	global_load_lds_dwordx4 v162, s[4:5]
	s_add_u32 m0, s62, 0x5000
	s_add_u32 s4, s56, 0x140000
	s_addc_u32 s5, s57, 0
	global_load_lds_dwordx4 v162, s[4:5]
	s_add_u32 m0, s62, 0x6000
	s_add_u32 s4, s56, 0x180000
	s_addc_u32 s5, s57, 0
	global_load_lds_dwordx4 v162, s[4:5]
	s_add_u32 m0, s62, 0x7000
	s_add_u32 s4, s56, 0x1c0000
	s_addc_u32 s5, s57, 0
	global_load_lds_dwordx4 v162, s[4:5]
	global_load_dwordx4 v[184:187], v160, s[58:59] offset:0
	global_load_dwordx4 v[188:191], v160, s[58:59] offset:1024
	global_load_dwordx4 v[192:195], v161, s[58:59] offset:0
	global_load_dwordx4 v[196:199], v161, s[58:59] offset:1024
	v_mov_b32_e32 v0, 0
	v_mov_b32_e32 v1, 0
	v_mov_b32_e32 v2, 0
	v_mov_b32_e32 v3, 0
	v_mov_b32_e32 v4, 0
	v_mov_b32_e32 v5, 0
	v_mov_b32_e32 v6, 0
	v_mov_b32_e32 v7, 0
	v_mov_b32_e32 v8, 0
	v_mov_b32_e32 v9, 0
	v_mov_b32_e32 v10, 0
	v_mov_b32_e32 v11, 0
	v_mov_b32_e32 v12, 0
	v_mov_b32_e32 v13, 0
	v_mov_b32_e32 v14, 0
	v_mov_b32_e32 v15, 0
	v_mov_b32_e32 v16, 0
	v_mov_b32_e32 v17, 0
	v_mov_b32_e32 v18, 0
	v_mov_b32_e32 v19, 0
	v_mov_b32_e32 v20, 0
	v_mov_b32_e32 v21, 0
	v_mov_b32_e32 v22, 0
	v_mov_b32_e32 v23, 0
	v_mov_b32_e32 v24, 0
	v_mov_b32_e32 v25, 0
	v_mov_b32_e32 v26, 0
	v_mov_b32_e32 v27, 0
	v_mov_b32_e32 v28, 0
	v_mov_b32_e32 v29, 0
	v_mov_b32_e32 v30, 0
	v_mov_b32_e32 v31, 0
	v_mov_b32_e32 v32, 0
	v_mov_b32_e32 v33, 0
	v_mov_b32_e32 v34, 0
	v_mov_b32_e32 v35, 0
	v_mov_b32_e32 v36, 0
	v_mov_b32_e32 v37, 0
	v_mov_b32_e32 v38, 0
	v_mov_b32_e32 v39, 0
	v_mov_b32_e32 v40, 0
	v_mov_b32_e32 v41, 0
	v_mov_b32_e32 v42, 0
	v_mov_b32_e32 v43, 0
	v_mov_b32_e32 v44, 0
	v_mov_b32_e32 v45, 0
	v_mov_b32_e32 v46, 0
	v_mov_b32_e32 v47, 0
	v_mov_b32_e32 v48, 0
	v_mov_b32_e32 v49, 0
	v_mov_b32_e32 v50, 0
	v_mov_b32_e32 v51, 0
	v_mov_b32_e32 v52, 0
	v_mov_b32_e32 v53, 0
	v_mov_b32_e32 v54, 0
	v_mov_b32_e32 v55, 0
	v_mov_b32_e32 v56, 0
	v_mov_b32_e32 v57, 0
	v_mov_b32_e32 v58, 0
	v_mov_b32_e32 v59, 0
	v_mov_b32_e32 v60, 0
	v_mov_b32_e32 v61, 0
	v_mov_b32_e32 v62, 0
	v_mov_b32_e32 v63, 0
	v_mov_b32_e32 v64, 0
	v_mov_b32_e32 v65, 0
	v_mov_b32_e32 v66, 0
	v_mov_b32_e32 v67, 0
	v_mov_b32_e32 v68, 0
	v_mov_b32_e32 v69, 0
	v_mov_b32_e32 v70, 0
	v_mov_b32_e32 v71, 0
	v_mov_b32_e32 v72, 0
	v_mov_b32_e32 v73, 0
	v_mov_b32_e32 v74, 0
	v_mov_b32_e32 v75, 0
	v_mov_b32_e32 v76, 0
	v_mov_b32_e32 v77, 0
	v_mov_b32_e32 v78, 0
	v_mov_b32_e32 v79, 0
	v_mov_b32_e32 v80, 0
	v_mov_b32_e32 v81, 0
	v_mov_b32_e32 v82, 0
	v_mov_b32_e32 v83, 0
	v_mov_b32_e32 v84, 0
	v_mov_b32_e32 v85, 0
	v_mov_b32_e32 v86, 0
	v_mov_b32_e32 v87, 0
	v_mov_b32_e32 v88, 0
	v_mov_b32_e32 v89, 0
	v_mov_b32_e32 v90, 0
	v_mov_b32_e32 v91, 0
	v_mov_b32_e32 v92, 0
	v_mov_b32_e32 v93, 0
	v_mov_b32_e32 v94, 0
	v_mov_b32_e32 v95, 0
	v_mov_b32_e32 v96, 0
	v_mov_b32_e32 v97, 0
	v_mov_b32_e32 v98, 0
	v_mov_b32_e32 v99, 0
	v_mov_b32_e32 v100, 0
	v_mov_b32_e32 v101, 0
	v_mov_b32_e32 v102, 0
	v_mov_b32_e32 v103, 0
	v_mov_b32_e32 v104, 0
	v_mov_b32_e32 v105, 0
	v_mov_b32_e32 v106, 0
	v_mov_b32_e32 v107, 0
	v_mov_b32_e32 v108, 0
	v_mov_b32_e32 v109, 0
	v_mov_b32_e32 v110, 0
	v_mov_b32_e32 v111, 0
	v_mov_b32_e32 v112, 0
	v_mov_b32_e32 v113, 0
	v_mov_b32_e32 v114, 0
	v_mov_b32_e32 v115, 0
	v_mov_b32_e32 v116, 0
	v_mov_b32_e32 v117, 0
	v_mov_b32_e32 v118, 0
	v_mov_b32_e32 v119, 0
	v_mov_b32_e32 v120, 0
	v_mov_b32_e32 v121, 0
	v_mov_b32_e32 v122, 0
	v_mov_b32_e32 v123, 0
	v_mov_b32_e32 v124, 0
	v_mov_b32_e32 v125, 0
	v_mov_b32_e32 v126, 0
	v_mov_b32_e32 v127, 0
	s_mov_b32 s63, 0
.Lg2_ff2_loop16:
	s_waitcnt vmcnt(0)
	s_barrier
	s_add_u32 s56, s56, 0x80
	s_addc_u32 s57, s57, 0
	s_add_u32 s58, s58, 0x800
	s_addc_u32 s59, s59, 0
	s_add_u32 m0, s62, 0x8800
	s_add_u32 s4, s56, 0x0
	s_addc_u32 s5, s57, 0
	global_load_lds_dwordx4 v162, s[4:5]
	s_add_u32 m0, s62, 0x9800
	s_add_u32 s4, s56, 0x40000
	s_addc_u32 s5, s57, 0
	global_load_lds_dwordx4 v162, s[4:5]
	s_add_u32 m0, s62, 0xa800
	s_add_u32 s4, s56, 0x80000
	s_addc_u32 s5, s57, 0
	global_load_lds_dwordx4 v162, s[4:5]
	s_add_u32 m0, s62, 0xb800
	s_add_u32 s4, s56, 0xc0000
	s_addc_u32 s5, s57, 0
	global_load_lds_dwordx4 v162, s[4:5]
	s_add_u32 m0, s62, 0xc800
	s_add_u32 s4, s56, 0x100000
	s_addc_u32 s5, s57, 0
	global_load_lds_dwordx4 v162, s[4:5]
	s_add_u32 m0, s62, 0xd800
	s_add_u32 s4, s56, 0x140000
	s_addc_u32 s5, s57, 0
	global_load_lds_dwordx4 v162, s[4:5]
	s_add_u32 m0, s62, 0xe800
	s_add_u32 s4, s56, 0x180000
	s_addc_u32 s5, s57, 0
	global_load_lds_dwordx4 v162, s[4:5]
	s_add_u32 m0, s62, 0xf800
	s_add_u32 s4, s56, 0x1c0000
	s_addc_u32 s5, s57, 0
	global_load_lds_dwordx4 v162, s[4:5]
	global_load_dwordx4 v[200:203], v160, s[58:59] offset:0
	global_load_dwordx4 v[204:207], v160, s[58:59] offset:1024
	global_load_dwordx4 v[208:211], v161, s[58:59] offset:0
	global_load_dwordx4 v[240:243], v161, s[58:59] offset:1024
	ds_read_b128 v[136:139], v156 offset:0
	ds_read_b128 v[140:143], v156 offset:2048
	ds_read_b128 v[144:147], v156 offset:4096
	ds_read_b128 v[148:151], v156 offset:6144
	ds_read_b128 v[164:167], v156 offset:8192
	ds_read_b128 v[168:171], v156 offset:10240
	ds_read_b128 v[172:175], v156 offset:12288
	ds_read_b128 v[176:179], v156 offset:14336
	s_waitcnt lgkmcnt(4)
	v_mfma_f32_16x16x32_bf16 v[0:3], v[184:187], v[136:139], v[0:3]
	v_mfma_f32_16x16x32_bf16 v[4:7], v[192:195], v[136:139], v[4:7]
	v_mfma_f32_16x16x32_bf16 v[8:11], v[184:187], v[140:143], v[8:11]
	v_mfma_f32_16x16x32_bf16 v[12:15], v[192:195], v[140:143], v[12:15]
	v_mfma_f32_16x16x32_bf16 v[16:19], v[184:187], v[144:147], v[16:19]
	v_mfma_f32_16x16x32_bf16 v[20:23], v[192:195], v[144:147], v[20:23]
	v_mfma_f32_16x16x32_bf16 v[24:27], v[184:187], v[148:151], v[24:27]
	v_mfma_f32_16x16x32_bf16 v[28:31], v[192:195], v[148:151], v[28:31]
	ds_read_b128 v[136:139], v156 offset:16384
	ds_read_b128 v[140:143], v156 offset:18432
	ds_read_b128 v[144:147], v156 offset:20480
	ds_read_b128 v[148:151], v156 offset:22528
	s_waitcnt lgkmcnt(4)
	v_mfma_f32_16x16x32_bf16 v[32:35], v[184:187], v[164:167], v[32:35]
	v_mfma_f32_16x16x32_bf16 v[36:39], v[192:195], v[164:167], v[36:39]
	v_mfma_f32_16x16x32_bf16 v[40:43], v[184:187], v[168:171], v[40:43]
	v_mfma_f32_16x16x32_bf16 v[44:47], v[192:195], v[168:171], v[44:47]
	v_mfma_f32_16x16x32_bf16 v[48:51], v[184:187], v[172:175], v[48:51]
	v_mfma_f32_16x16x32_bf16 v[52:55], v[192:195], v[172:175], v[52:55]
	v_mfma_f32_16x16x32_bf16 v[56:59], v[184:187], v[176:179], v[56:59]
	v_mfma_f32_16x16x32_bf16 v[60:63], v[192:195], v[176:179], v[60:63]
	ds_read_b128 v[164:167], v156 offset:24576
	ds_read_b128 v[168:171], v156 offset:26624
	ds_read_b128 v[172:175], v156 offset:28672
	ds_read_b128 v[176:179], v156 offset:30720
	s_waitcnt lgkmcnt(4)
	v_mfma_f32_16x16x32_bf16 v[64:67], v[184:187], v[136:139], v[64:67]
	v_mfma_f32_16x16x32_bf16 v[68:71], v[192:195], v[136:139], v[68:71]
	v_mfma_f32_16x16x32_bf16 v[72:75], v[184:187], v[140:143], v[72:75]
	v_mfma_f32_16x16x32_bf16 v[76:79], v[192:195], v[140:143], v[76:79]
	v_mfma_f32_16x16x32_bf16 v[80:83], v[184:187], v[144:147], v[80:83]
	v_mfma_f32_16x16x32_bf16 v[84:87], v[192:195], v[144:147], v[84:87]
	v_mfma_f32_16x16x32_bf16 v[88:91], v[184:187], v[148:151], v[88:91]
	v_mfma_f32_16x16x32_bf16 v[92:95], v[192:195], v[148:151], v[92:95]
	ds_read_b128 v[136:139], v157 offset:0
	ds_read_b128 v[140:143], v157 offset:2048
	ds_read_b128 v[144:147], v157 offset:4096
	ds_read_b128 v[148:151], v157 offset:6144
	s_waitcnt lgkmcnt(4)
	v_mfma_f32_16x16x32_bf16 v[96:99], v[184:187], v[164:167], v[96:99]
	v_mfma_f32_16x16x32_bf16 v[100:103], v[192:195], v[164:167], v[100:103]
	v_mfma_f32_16x16x32_bf16 v[104:107], v[184:187], v[168:171], v[104:107]
	v_mfma_f32_16x16x32_bf16 v[108:111], v[192:195], v[168:171], v[108:111]
	v_mfma_f32_16x16x32_bf16 v[112:115], v[184:187], v[172:175], v[112:115]
	v_mfma_f32_16x16x32_bf16 v[116:119], v[192:195], v[172:175], v[116:119]
	v_mfma_f32_16x16x32_bf16 v[120:123], v[184:187], v[176:179], v[120:123]
	v_mfma_f32_16x16x32_bf16 v[124:127], v[192:195], v[176:179], v[124:127]
	ds_read_b128 v[164:167], v157 offset:8192
	ds_read_b128 v[168:171], v157 offset:10240
	ds_read_b128 v[172:175], v157 offset:12288
	ds_read_b128 v[176:179], v157 offset:14336
	s_waitcnt lgkmcnt(4)
	v_mfma_f32_16x16x32_bf16 v[0:3], v[188:191], v[136:139], v[0:3]
	v_mfma_f32_16x16x32_bf16 v[4:7], v[196:199], v[136:139], v[4:7]
	v_mfma_f32_16x16x32_bf16 v[8:11], v[188:191], v[140:143], v[8:11]
	v_mfma_f32_16x16x32_bf16 v[12:15], v[196:199], v[140:143], v[12:15]
	v_mfma_f32_16x16x32_bf16 v[16:19], v[188:191], v[144:147], v[16:19]
	v_mfma_f32_16x16x32_bf16 v[20:23], v[196:199], v[144:147], v[20:23]
	v_mfma_f32_16x16x32_bf16 v[24:27], v[188:191], v[148:151], v[24:27]
	v_mfma_f32_16x16x32_bf16 v[28:31], v[196:199], v[148:151], v[28:31]
	ds_read_b128 v[136:139], v157 offset:16384
	ds_read_b128 v[140:143], v157 offset:18432
	ds_read_b128 v[144:147], v157 offset:20480
	ds_read_b128 v[148:151], v157 offset:22528
	s_waitcnt lgkmcnt(4)
	v_mfma_f32_16x16x32_bf16 v[32:35], v[188:191], v[164:167], v[32:35]
	v_mfma_f32_16x16x32_bf16 v[36:39], v[196:199], v[164:167], v[36:39]
	v_mfma_f32_16x16x32_bf16 v[40:43], v[188:191], v[168:171], v[40:43]
	v_mfma_f32_16x16x32_bf16 v[44:47], v[196:199], v[168:171], v[44:47]
	v_mfma_f32_16x16x32_bf16 v[48:51], v[188:191], v[172:175], v[48:51]
	v_mfma_f32_16x16x32_bf16 v[52:55], v[196:199], v[172:175], v[52:55]
	v_mfma_f32_16x16x32_bf16 v[56:59], v[188:191], v[176:179], v[56:59]
	v_mfma_f32_16x16x32_bf16 v[60:63], v[196:199], v[176:179], v[60:63]
	ds_read_b128 v[164:167], v157 offset:24576
	ds_read_b128 v[168:171], v157 offset:26624
	ds_read_b128 v[172:175], v157 offset:28672
	ds_read_b128 v[176:179], v157 offset:30720
	s_waitcnt lgkmcnt(4)
	v_mfma_f32_16x16x32_bf16 v[64:67], v[188:191], v[136:139], v[64:67]
	v_mfma_f32_16x16x32_bf16 v[68:71], v[196:199], v[136:139], v[68:71]
	v_mfma_f32_16x16x32_bf16 v[72:75], v[188:191], v[140:143], v[72:75]
	v_mfma_f32_16x16x32_bf16 v[76:79], v[196:199], v[140:143], v[76:79]
	v_mfma_f32_16x16x32_bf16 v[80:83], v[188:191], v[144:147], v[80:83]
	v_mfma_f32_16x16x32_bf16 v[84:87], v[196:199], v[144:147], v[84:87]
	v_mfma_f32_16x16x32_bf16 v[88:91], v[188:191], v[148:151], v[88:91]
	v_mfma_f32_16x16x32_bf16 v[92:95], v[196:199], v[148:151], v[92:95]
	s_waitcnt lgkmcnt(0)
	v_mfma_f32_16x16x32_bf16 v[96:99], v[188:191], v[164:167], v[96:99]
	v_mfma_f32_16x16x32_bf16 v[100:103], v[196:199], v[164:167], v[100:103]
	v_mfma_f32_16x16x32_bf16 v[104:107], v[188:191], v[168:171], v[104:107]
	v_mfma_f32_16x16x32_bf16 v[108:111], v[196:199], v[168:171], v[108:111]
	v_mfma_f32_16x16x32_bf16 v[112:115], v[188:191], v[172:175], v[112:115]
	v_mfma_f32_16x16x32_bf16 v[116:119], v[196:199], v[172:175], v[116:119]
	v_mfma_f32_16x16x32_bf16 v[120:123], v[188:191], v[176:179], v[120:123]
	v_mfma_f32_16x16x32_bf16 v[124:127], v[196:199], v[176:179], v[124:127]
	s_waitcnt vmcnt(0)
	s_barrier
	s_cmp_ge_u32 s63, 62
	s_cbranch_scc1 .Lg2_ff2_noissue16
	s_add_u32 s56, s56, 0x80
	s_addc_u32 s57, s57, 0
	s_add_u32 s58, s58, 0x800
	s_addc_u32 s59, s59, 0
	s_add_u32 m0, s62, 0x0
	s_add_u32 s4, s56, 0x0
	s_addc_u32 s5, s57, 0
	global_load_lds_dwordx4 v162, s[4:5]
	s_add_u32 m0, s62, 0x1000
	s_add_u32 s4, s56, 0x40000
	s_addc_u32 s5, s57, 0
	global_load_lds_dwordx4 v162, s[4:5]
	s_add_u32 m0, s62, 0x2000
	s_add_u32 s4, s56, 0x80000
	s_addc_u32 s5, s57, 0
	global_load_lds_dwordx4 v162, s[4:5]
	s_add_u32 m0, s62, 0x3000
	s_add_u32 s4, s56, 0xc0000
	s_addc_u32 s5, s57, 0
	global_load_lds_dwordx4 v162, s[4:5]
	s_add_u32 m0, s62, 0x4000
	s_add_u32 s4, s56, 0x100000
	s_addc_u32 s5, s57, 0
	global_load_lds_dwordx4 v162, s[4:5]
	s_add_u32 m0, s62, 0x5000
	s_add_u32 s4, s56, 0x140000
	s_addc_u32 s5, s57, 0
	global_load_lds_dwordx4 v162, s[4:5]
	s_add_u32 m0, s62, 0x6000
	s_add_u32 s4, s56, 0x180000
	s_addc_u32 s5, s57, 0
	global_load_lds_dwordx4 v162, s[4:5]
	s_add_u32 m0, s62, 0x7000
	s_add_u32 s4, s56, 0x1c0000
	s_addc_u32 s5, s57, 0
	global_load_lds_dwordx4 v162, s[4:5]
	global_load_dwordx4 v[184:187], v160, s[58:59] offset:0
	global_load_dwordx4 v[188:191], v160, s[58:59] offset:1024
	global_load_dwordx4 v[192:195], v161, s[58:59] offset:0
	global_load_dwordx4 v[196:199], v161, s[58:59] offset:1024

.Lg2_ff2_rd_lastaP:
	s_waitcnt lgkmcnt(15)
	global_store_dwordx4 v252, v[0:3], s[60:61]
	s_add_u32 s60, s60, 0x8000
	s_addc_u32 s61, s61, 0
	s_waitcnt lgkmcnt(14)
	global_store_dwordx4 v252, v[4:7], s[60:61]
	s_add_u32 s60, s60, 0x8000
	s_addc_u32 s61, s61, 0
	s_waitcnt lgkmcnt(13)
	global_store_dwordx4 v252, v[8:11], s[60:61]
	s_add_u32 s60, s60, 0x8000
	s_addc_u32 s61, s61, 0
	s_waitcnt lgkmcnt(12)
	global_store_dwordx4 v252, v[12:15], s[60:61]
	s_add_u32 s60, s60, 0x8000
	s_addc_u32 s61, s61, 0
	s_waitcnt lgkmcnt(11)
	global_store_dwordx4 v252, v[16:19], s[60:61]
	s_add_u32 s60, s60, 0x8000
	s_addc_u32 s61, s61, 0
	s_waitcnt lgkmcnt(10)
	global_store_dwordx4 v252, v[20:23], s[60:61]
	s_add_u32 s60, s60, 0x8000
	s_addc_u32 s61, s61, 0
	s_waitcnt lgkmcnt(9)
	global_store_dwordx4 v252, v[24:27], s[60:61]
	s_add_u32 s60, s60, 0x8000
	s_addc_u32 s61, s61, 0
	s_waitcnt lgkmcnt(8)
	global_store_dwordx4 v252, v[28:31], s[60:61]
	s_add_u32 s60, s60, 0x8000
	s_addc_u32 s61, s61, 0
	s_waitcnt lgkmcnt(7)
	global_store_dwordx4 v252, v[32:35], s[60:61]
	s_add_u32 s60, s60, 0x8000
	s_addc_u32 s61, s61, 0
	s_waitcnt lgkmcnt(6)
	global_store_dwordx4 v252, v[36:39], s[60:61]
	s_add_u32 s60, s60, 0x8000
	s_addc_u32 s61, s61, 0
	s_waitcnt lgkmcnt(5)
	global_store_dwordx4 v252, v[40:43], s[60:61]
	s_add_u32 s60, s60, 0x8000
	s_addc_u32 s61, s61, 0
	s_waitcnt lgkmcnt(4)
	global_store_dwordx4 v252, v[44:47], s[60:61]
	s_add_u32 s60, s60, 0x8000
	s_addc_u32 s61, s61, 0
	s_waitcnt lgkmcnt(3)
	global_store_dwordx4 v252, v[48:51], s[60:61]
	s_add_u32 s60, s60, 0x8000
	s_addc_u32 s61, s61, 0
	s_waitcnt lgkmcnt(2)
	global_store_dwordx4 v252, v[52:55], s[60:61]
	s_add_u32 s60, s60, 0x8000
	s_addc_u32 s61, s61, 0
	s_waitcnt lgkmcnt(1)
	global_store_dwordx4 v252, v[56:59], s[60:61]
	s_add_u32 s60, s60, 0x8000
	s_addc_u32 s61, s61, 0
	s_waitcnt lgkmcnt(0)
	global_store_dwordx4 v252, v[60:63], s[60:61]
	s_add_u32 s60, s60, 0x8000
	s_addc_u32 s61, s61, 0
	s_cmp_eq_u32 s65, 0
	s_cbranch_scc1 .Lg2_ff2_rd_lastP
	s_waitcnt lgkmcnt(0)
	global_store_dwordx4 v252, v[64:67], s[60:61]
	s_add_u32 s60, s60, 0x8000
	s_addc_u32 s61, s61, 0

.Lg2_ff1_tile:
	s_lshl_b32 s0, s64, 3
	s_add_i32 s38, s0, s68
	s_mov_b32 s69, s42
	s_mov_b32 s65, s43
	s_lshl_b32 s0, s38, 7
	s_mul_i32 s2, s69, 0x800
	s_mul_hi_u32 s3, s69, 0x800
	s_add_u32 s56, s26, s2
	s_addc_u32 s57, s27, s3
	s_add_u32 s56, s56, 0x13240000
	s_addc_u32 s57, s57, 0
	s_mul_i32 s2, s0, 0x800
	s_mul_hi_u32 s3, s0, 0x800
	s_add_u32 s58, s26, s2
	s_addc_u32 s59, s27, s3
	s_add_u32 s58, s58, 0xff40000
	s_addc_u32 s59, s59, 0
	s_mul_i32 s2, s69, 0x2000
	s_mul_hi_u32 s3, s69, 0x2000
	s_lshl_b32 s0, s0, 1
	s_add_u32 s2, s2, s0
	s_addc_u32 s3, s3, 0
	s_add_u32 s60, s26, s2
	s_addc_u32 s61, s27, s3
	s_add_u32 s60, s60, 0x0
	s_addc_u32 s61, s61, 0
	s_cmp_eq_u32 s65, 0
	s_cbranch_scc1 .Lg2_ff1_k16
	s_add_u32 m0, s62, 0x0
	s_add_u32 s4, s56, 0x0
	s_addc_u32 s5, s57, 0
	global_load_lds_dwordx4 v162, s[4:5]
	s_add_u32 m0, s62, 0x1000
	s_add_u32 s4, s56, 0x10000
	s_addc_u32 s5, s57, 0
	global_load_lds_dwordx4 v162, s[4:5]
	s_add_u32 m0, s62, 0x2000
	s_add_u32 s4, s56, 0x20000
	s_addc_u32 s5, s57, 0
	global_load_lds_dwordx4 v162, s[4:5]
	s_add_u32 m0, s62, 0x3000
	s_add_u32 s4, s56, 0x30000
	s_addc_u32 s5, s57, 0
	global_load_lds_dwordx4 v162, s[4:5]
	s_add_u32 m0, s62, 0x4000
	s_add_u32 s4, s56, 0x40000
	s_addc_u32 s5, s57, 0
	global_load_lds_dwordx4 v162, s[4:5]
	s_add_u32 m0, s62, 0x5000
	s_add_u32 s4, s56, 0x50000
	s_addc_u32 s5, s57, 0
	global_load_lds_dwordx4 v162, s[4:5]
	s_add_u32 m0, s62, 0x6000
	s_add_u32 s4, s56, 0x60000
	s_addc_u32 s5, s57, 0
	global_load_lds_dwordx4 v162, s[4:5]
	s_add_u32 m0, s62, 0x7000
	s_add_u32 s4, s56, 0x70000
	s_addc_u32 s5, s57, 0
	global_load_lds_dwordx4 v162, s[4:5]
	s_cmp_gt_u32 s70, 1
	s_cbranch_scc1 .Lg2_ff1_nodma_0
	s_add_u32 m0, s62, 0x8000
	s_add_u32 s4, s56, 0x80000
	s_addc_u32 s5, s57, 0
	global_load_lds_dwordx4 v162, s[4:5]

.Lg2_ff1_loop17:
	s_waitcnt vmcnt(0)
	s_barrier
	s_add_u32 s56, s56, 0x80
	s_addc_u32 s57, s57, 0
	s_add_u32 s58, s58, 0x800
	s_addc_u32 s59, s59, 0
	s_add_u32 m0, s62, 0x8800
	s_add_u32 s4, s56, 0x0
	s_addc_u32 s5, s57, 0
	global_load_lds_dwordx4 v162, s[4:5]
	s_add_u32 m0, s62, 0x9800
	s_add_u32 s4, s56, 0x10000
	s_addc_u32 s5, s57, 0
	global_load_lds_dwordx4 v162, s[4:5]
	s_add_u32 m0, s62, 0xa800
	s_add_u32 s4, s56, 0x20000
	s_addc_u32 s5, s57, 0
	global_load_lds_dwordx4 v162, s[4:5]
	s_add_u32 m0, s62, 0xb800
	s_add_u32 s4, s56, 0x30000
	s_addc_u32 s5, s57, 0
	global_load_lds_dwordx4 v162, s[4:5]
	s_add_u32 m0, s62, 0xc800
	s_add_u32 s4, s56, 0x40000
	s_addc_u32 s5, s57, 0
	global_load_lds_dwordx4 v162, s[4:5]
	s_add_u32 m0, s62, 0xd800
	s_add_u32 s4, s56, 0x50000
	s_addc_u32 s5, s57, 0
	global_load_lds_dwordx4 v162, s[4:5]
	s_add_u32 m0, s62, 0xe800
	s_add_u32 s4, s56, 0x60000
	s_addc_u32 s5, s57, 0
	global_load_lds_dwordx4 v162, s[4:5]
	s_add_u32 m0, s62, 0xf800
	s_add_u32 s4, s56, 0x70000
	s_addc_u32 s5, s57, 0
	global_load_lds_dwordx4 v162, s[4:5]
	s_cmp_gt_u32 s70, 1
	s_cbranch_scc1 .Lg2_ff1_nodma_1
	s_add_u32 m0, s62, 0x10800
	s_add_u32 s4, s56, 0x80000
	s_addc_u32 s5, s57, 0
	global_load_lds_dwordx4 v162, s[4:5]
.Lg2_ff1_nodma_1:
	global_load_dwordx4 v[200:203], v160, s[58:59] offset:0
	global_load_dwordx4 v[204:207], v160, s[58:59] offset:1024
	global_load_dwordx4 v[208:211], v161, s[58:59] offset:0
	global_load_dwordx4 v[240:243], v161, s[58:59] offset:1024
	ds_read_b128 v[136:139], v156 offset:0
	ds_read_b128 v[140:143], v156 offset:2048
	ds_read_b128 v[144:147], v156 offset:4096
	ds_read_b128 v[148:151], v156 offset:6144
	ds_read_b128 v[164:167], v156 offset:8192
	ds_read_b128 v[168:171], v156 offset:10240
	ds_read_b128 v[172:175], v156 offset:12288
	ds_read_b128 v[176:179], v156 offset:14336
	s_waitcnt lgkmcnt(4)
	v_mfma_f32_16x16x32_bf16 v[0:3], v[184:187], v[136:139], v[0:3]
	v_mfma_f32_16x16x32_bf16 v[4:7], v[192:195], v[136:139], v[4:7]
	v_mfma_f32_16x16x32_bf16 v[8:11], v[184:187], v[140:143], v[8:11]
	v_mfma_f32_16x16x32_bf16 v[12:15], v[192:195], v[140:143], v[12:15]
	v_mfma_f32_16x16x32_bf16 v[16:19], v[184:187], v[144:147], v[16:19]
	v_mfma_f32_16x16x32_bf16 v[20:23], v[192:195], v[144:147], v[20:23]
	v_mfma_f32_16x16x32_bf16 v[24:27], v[184:187], v[148:151], v[24:27]
	v_mfma_f32_16x16x32_bf16 v[28:31], v[192:195], v[148:151], v[28:31]
	ds_read_b128 v[136:139], v156 offset:16384
	ds_read_b128 v[140:143], v156 offset:18432
	ds_read_b128 v[144:147], v156 offset:20480
	ds_read_b128 v[148:151], v156 offset:22528
	s_waitcnt lgkmcnt(4)
	v_mfma_f32_16x16x32_bf16 v[32:35], v[184:187], v[164:167], v[32:35]
	v_mfma_f32_16x16x32_bf16 v[36:39], v[192:195], v[164:167], v[36:39]
	v_mfma_f32_16x16x32_bf16 v[40:43], v[184:187], v[168:171], v[40:43]
	v_mfma_f32_16x16x32_bf16 v[44:47], v[192:195], v[168:171], v[44:47]
	v_mfma_f32_16x16x32_bf16 v[48:51], v[184:187], v[172:175], v[48:51]
	v_mfma_f32_16x16x32_bf16 v[52:55], v[192:195], v[172:175], v[52:55]
	v_mfma_f32_16x16x32_bf16 v[56:59], v[184:187], v[176:179], v[56:59]
	v_mfma_f32_16x16x32_bf16 v[60:63], v[192:195], v[176:179], v[60:63]
	ds_read_b128 v[164:167], v156 offset:24576
	ds_read_b128 v[168:171], v156 offset:26624
	ds_read_b128 v[172:175], v156 offset:28672
	ds_read_b128 v[176:179], v156 offset:30720
	ds_read_b128 v[180:183], v156 offset:32768
	s_waitcnt lgkmcnt(5)
	v_mfma_f32_16x16x32_bf16 v[64:67], v[184:187], v[136:139], v[64:67]
	v_mfma_f32_16x16x32_bf16 v[68:71], v[192:195], v[136:139], v[68:71]
	v_mfma_f32_16x16x32_bf16 v[72:75], v[184:187], v[140:143], v[72:75]
	v_mfma_f32_16x16x32_bf16 v[76:79], v[192:195], v[140:143], v[76:79]
	v_mfma_f32_16x16x32_bf16 v[80:83], v[184:187], v[144:147], v[80:83]
	v_mfma_f32_16x16x32_bf16 v[84:87], v[192:195], v[144:147], v[84:87]
	v_mfma_f32_16x16x32_bf16 v[88:91], v[184:187], v[148:151], v[88:91]
	v_mfma_f32_16x16x32_bf16 v[92:95], v[192:195], v[148:151], v[92:95]
	ds_read_b128 v[136:139], v157 offset:0
	ds_read_b128 v[140:143], v157 offset:2048
	ds_read_b128 v[144:147], v157 offset:4096
	ds_read_b128 v[148:151], v157 offset:6144
	s_waitcnt lgkmcnt(4)
	v_mfma_f32_16x16x32_bf16 v[96:99], v[184:187], v[164:167], v[96:99]
	v_mfma_f32_16x16x32_bf16 v[100:103], v[192:195], v[164:167], v[100:103]
	v_mfma_f32_16x16x32_bf16 v[104:107], v[184:187], v[168:171], v[104:107]
	v_mfma_f32_16x16x32_bf16 v[108:111], v[192:195], v[168:171], v[108:111]
	v_mfma_f32_16x16x32_bf16 v[112:115], v[184:187], v[172:175], v[112:115]
	v_mfma_f32_16x16x32_bf16 v[116:119], v[192:195], v[172:175], v[116:119]
	v_mfma_f32_16x16x32_bf16 v[120:123], v[184:187], v[176:179], v[120:123]
	v_mfma_f32_16x16x32_bf16 v[124:127], v[192:195], v[176:179], v[124:127]
	v_mfma_f32_16x16x32_bf16 v[128:131], v[184:187], v[180:183], v[128:131]
	v_mfma_f32_16x16x32_bf16 v[132:135], v[192:195], v[180:183], v[132:135]
	ds_read_b128 v[164:167], v157 offset:8192
	ds_read_b128 v[168:171], v157 offset:10240
	ds_read_b128 v[172:175], v157 offset:12288
	ds_read_b128 v[176:179], v157 offset:14336
	s_waitcnt lgkmcnt(4)
	v_mfma_f32_16x16x32_bf16 v[0:3], v[188:191], v[136:139], v[0:3]
	v_mfma_f32_16x16x32_bf16 v[4:7], v[196:199], v[136:139], v[4:7]
	v_mfma_f32_16x16x32_bf16 v[8:11], v[188:191], v[140:143], v[8:11]
	v_mfma_f32_16x16x32_bf16 v[12:15], v[196:199], v[140:143], v[12:15]
	v_mfma_f32_16x16x32_bf16 v[16:19], v[188:191], v[144:147], v[16:19]
	v_mfma_f32_16x16x32_bf16 v[20:23], v[196:199], v[144:147], v[20:23]
	v_mfma_f32_16x16x32_bf16 v[24:27], v[188:191], v[148:151], v[24:27]
	v_mfma_f32_16x16x32_bf16 v[28:31], v[196:199], v[148:151], v[28:31]
	ds_read_b128 v[136:139], v157 offset:16384
	ds_read_b128 v[140:143], v157 offset:18432
	ds_read_b128 v[144:147], v157 offset:20480
	ds_read_b128 v[148:151], v157 offset:22528
	s_waitcnt lgkmcnt(4)
	v_mfma_f32_16x16x32_bf16 v[32:35], v[188:191], v[164:167], v[32:35]
	v_mfma_f32_16x16x32_bf16 v[36:39], v[196:199], v[164:167], v[36:39]
	v_mfma_f32_16x16x32_bf16 v[40:43], v[188:191], v[168:171], v[40:43]
	v_mfma_f32_16x16x32_bf16 v[44:47], v[196:199], v[168:171], v[44:47]
	v_mfma_f32_16x16x32_bf16 v[48:51], v[188:191], v[172:175], v[48:51]
	v_mfma_f32_16x16x32_bf16 v[52:55], v[196:199], v[172:175], v[52:55]
	v_mfma_f32_16x16x32_bf16 v[56:59], v[188:191], v[176:179], v[56:59]
	v_mfma_f32_16x16x32_bf16 v[60:63], v[196:199], v[176:179], v[60:63]
	ds_read_b128 v[164:167], v157 offset:24576
	ds_read_b128 v[168:171], v157 offset:26624
	ds_read_b128 v[172:175], v157 offset:28672
	ds_read_b128 v[176:179], v157 offset:30720
	ds_read_b128 v[180:183], v157 offset:32768
	s_waitcnt lgkmcnt(5)
	v_mfma_f32_16x16x32_bf16 v[64:67], v[188:191], v[136:139], v[64:67]
	v_mfma_f32_16x16x32_bf16 v[68:71], v[196:199], v[136:139], v[68:71]
	v_mfma_f32_16x16x32_bf16 v[72:75], v[188:191], v[140:143], v[72:75]
	v_mfma_f32_16x16x32_bf16 v[76:79], v[196:199], v[140:143], v[76:79]
	v_mfma_f32_16x16x32_bf16 v[80:83], v[188:191], v[144:147], v[80:83]
	v_mfma_f32_16x16x32_bf16 v[84:87], v[196:199], v[144:147], v[84:87]
	v_mfma_f32_16x16x32_bf16 v[88:91], v[188:191], v[148:151], v[88:91]
	v_mfma_f32_16x16x32_bf16 v[92:95], v[196:199], v[148:151], v[92:95]
	s_waitcnt lgkmcnt(0)
	v_mfma_f32_16x16x32_bf16 v[96:99], v[188:191], v[164:167], v[96:99]
	v_mfma_f32_16x16x32_bf16 v[100:103], v[196:199], v[164:167], v[100:103]
	v_mfma_f32_16x16x32_bf16 v[104:107], v[188:191], v[168:171], v[104:107]
	v_mfma_f32_16x16x32_bf16 v[108:111], v[196:199], v[168:171], v[108:111]
	v_mfma_f32_16x16x32_bf16 v[112:115], v[188:191], v[172:175], v[112:115]
	v_mfma_f32_16x16x32_bf16 v[116:119], v[196:199], v[172:175], v[116:119]
	v_mfma_f32_16x16x32_bf16 v[120:123], v[188:191], v[176:179], v[120:123]
	v_mfma_f32_16x16x32_bf16 v[124:127], v[196:199], v[176:179], v[124:127]
	v_mfma_f32_16x16x32_bf16 v[128:131], v[188:191], v[180:183], v[128:131]
	v_mfma_f32_16x16x32_bf16 v[132:135], v[196:199], v[180:183], v[132:135]
	s_waitcnt vmcnt(0)
	s_barrier
	s_cmp_ge_u32 s63, 14
	s_cbranch_scc1 .Lg2_ff1_noissue17
	s_add_u32 s56, s56, 0x80
	s_addc_u32 s57, s57, 0
	s_add_u32 s58, s58, 0x800
	s_addc_u32 s59, s59, 0
	s_add_u32 m0, s62, 0x0
	s_add_u32 s4, s56, 0x0
	s_addc_u32 s5, s57, 0
	global_load_lds_dwordx4 v162, s[4:5]
	s_add_u32 m0, s62, 0x1000
	s_add_u32 s4, s56, 0x10000
	s_addc_u32 s5, s57, 0
	global_load_lds_dwordx4 v162, s[4:5]
	s_add_u32 m0, s62, 0x2000
	s_add_u32 s4, s56, 0x20000
	s_addc_u32 s5, s57, 0
	global_load_lds_dwordx4 v162, s[4:5]
	s_add_u32 m0, s62, 0x3000
	s_add_u32 s4, s56, 0x30000
	s_addc_u32 s5, s57, 0
	global_load_lds_dwordx4 v162, s[4:5]
	s_add_u32 m0, s62, 0x4000
	s_add_u32 s4, s56, 0x40000
	s_addc_u32 s5, s57, 0
	global_load_lds_dwordx4 v162, s[4:5]
	s_add_u32 m0, s62, 0x5000
	s_add_u32 s4, s56, 0x50000
	s_addc_u32 s5, s57, 0
	global_load_lds_dwordx4 v162, s[4:5]
	s_add_u32 m0, s62, 0x6000
	s_add_u32 s4, s56, 0x60000
	s_addc_u32 s5, s57, 0
	global_load_lds_dwordx4 v162, s[4:5]
	s_add_u32 m0, s62, 0x7000
	s_add_u32 s4, s56, 0x70000
	s_addc_u32 s5, s57, 0
	global_load_lds_dwordx4 v162, s[4:5]
	s_cmp_gt_u32 s70, 1
	s_cbranch_scc1 .Lg2_ff1_nodma_2
	s_add_u32 m0, s62, 0x8000
	s_add_u32 s4, s56, 0x80000
	s_addc_u32 s5, s57, 0
	global_load_lds_dwordx4 v162, s[4:5]

.Lg2_ff1_k16:
	s_add_u32 m0, s62, 0x0
	s_add_u32 s4, s56, 0x0
	s_addc_u32 s5, s57, 0
	global_load_lds_dwordx4 v162, s[4:5]
	s_add_u32 m0, s62, 0x1000
	s_add_u32 s4, s56, 0x10000
	s_addc_u32 s5, s57, 0
	global_load_lds_dwordx4 v162, s[4:5]
	s_add_u32 m0, s62, 0x2000
	s_add_u32 s4, s56, 0x20000
	s_addc_u32 s5, s57, 0
	global_load_lds_dwordx4 v162, s[4:5]
	s_add_u32 m0, s62, 0x3000
	s_add_u32 s4, s56, 0x30000
	s_addc_u32 s5, s57, 0
	global_load_lds_dwordx4 v162, s[4:5]
	s_add_u32 m0, s62, 0x4000
	s_add_u32 s4, s56, 0x40000
	s_addc_u32 s5, s57, 0
	global_load_lds_dwordx4 v162, s[4:5]
	s_add_u32 m0, s62, 0x5000
	s_add_u32 s4, s56, 0x50000
	s_addc_u32 s5, s57, 0
	global_load_lds_dwordx4 v162, s[4:5]
	s_add_u32 m0, s62, 0x6000
	s_add_u32 s4, s56, 0x60000
	s_addc_u32 s5, s57, 0
	global_load_lds_dwordx4 v162, s[4:5]
	s_add_u32 m0, s62, 0x7000
	s_add_u32 s4, s56, 0x70000
	s_addc_u32 s5, s57, 0
	global_load_lds_dwordx4 v162, s[4:5]
	global_load_dwordx4 v[184:187], v160, s[58:59] offset:0
	global_load_dwordx4 v[188:191], v160, s[58:59] offset:1024
	global_load_dwordx4 v[192:195], v161, s[58:59] offset:0
	global_load_dwordx4 v[196:199], v161, s[58:59] offset:1024
	v_mov_b32_e32 v0, 0
	v_mov_b32_e32 v1, 0
	v_mov_b32_e32 v2, 0
	v_mov_b32_e32 v3, 0
	v_mov_b32_e32 v4, 0
	v_mov_b32_e32 v5, 0
	v_mov_b32_e32 v6, 0
	v_mov_b32_e32 v7, 0
	v_mov_b32_e32 v8, 0
	v_mov_b32_e32 v9, 0
	v_mov_b32_e32 v10, 0
	v_mov_b32_e32 v11, 0
	v_mov_b32_e32 v12, 0
	v_mov_b32_e32 v13, 0
	v_mov_b32_e32 v14, 0
	v_mov_b32_e32 v15, 0
	v_mov_b32_e32 v16, 0
	v_mov_b32_e32 v17, 0
	v_mov_b32_e32 v18, 0
	v_mov_b32_e32 v19, 0
	v_mov_b32_e32 v20, 0
	v_mov_b32_e32 v21, 0
	v_mov_b32_e32 v22, 0
	v_mov_b32_e32 v23, 0
	v_mov_b32_e32 v24, 0
	v_mov_b32_e32 v25, 0
	v_mov_b32_e32 v26, 0
	v_mov_b32_e32 v27, 0
	v_mov_b32_e32 v28, 0
	v_mov_b32_e32 v29, 0
	v_mov_b32_e32 v30, 0
	v_mov_b32_e32 v31, 0
	v_mov_b32_e32 v32, 0
	v_mov_b32_e32 v33, 0
	v_mov_b32_e32 v34, 0
	v_mov_b32_e32 v35, 0
	v_mov_b32_e32 v36, 0
	v_mov_b32_e32 v37, 0
	v_mov_b32_e32 v38, 0
	v_mov_b32_e32 v39, 0
	v_mov_b32_e32 v40, 0
	v_mov_b32_e32 v41, 0
	v_mov_b32_e32 v42, 0
	v_mov_b32_e32 v43, 0
	v_mov_b32_e32 v44, 0
	v_mov_b32_e32 v45, 0
	v_mov_b32_e32 v46, 0
	v_mov_b32_e32 v47, 0
	v_mov_b32_e32 v48, 0
	v_mov_b32_e32 v49, 0
	v_mov_b32_e32 v50, 0
	v_mov_b32_e32 v51, 0
	v_mov_b32_e32 v52, 0
	v_mov_b32_e32 v53, 0
	v_mov_b32_e32 v54, 0
	v_mov_b32_e32 v55, 0
	v_mov_b32_e32 v56, 0
	v_mov_b32_e32 v57, 0
	v_mov_b32_e32 v58, 0
	v_mov_b32_e32 v59, 0
	v_mov_b32_e32 v60, 0
	v_mov_b32_e32 v61, 0
	v_mov_b32_e32 v62, 0
	v_mov_b32_e32 v63, 0
	v_mov_b32_e32 v64, 0
	v_mov_b32_e32 v65, 0
	v_mov_b32_e32 v66, 0
	v_mov_b32_e32 v67, 0
	v_mov_b32_e32 v68, 0
	v_mov_b32_e32 v69, 0
	v_mov_b32_e32 v70, 0
	v_mov_b32_e32 v71, 0
	v_mov_b32_e32 v72, 0
	v_mov_b32_e32 v73, 0
	v_mov_b32_e32 v74, 0
	v_mov_b32_e32 v75, 0
	v_mov_b32_e32 v76, 0
	v_mov_b32_e32 v77, 0
	v_mov_b32_e32 v78, 0
	v_mov_b32_e32 v79, 0
	v_mov_b32_e32 v80, 0
	v_mov_b32_e32 v81, 0
	v_mov_b32_e32 v82, 0
	v_mov_b32_e32 v83, 0
	v_mov_b32_e32 v84, 0
	v_mov_b32_e32 v85, 0
	v_mov_b32_e32 v86, 0
	v_mov_b32_e32 v87, 0
	v_mov_b32_e32 v88, 0
	v_mov_b32_e32 v89, 0
	v_mov_b32_e32 v90, 0
	v_mov_b32_e32 v91, 0
	v_mov_b32_e32 v92, 0
	v_mov_b32_e32 v93, 0
	v_mov_b32_e32 v94, 0
	v_mov_b32_e32 v95, 0
	v_mov_b32_e32 v96, 0
	v_mov_b32_e32 v97, 0
	v_mov_b32_e32 v98, 0
	v_mov_b32_e32 v99, 0
	v_mov_b32_e32 v100, 0
	v_mov_b32_e32 v101, 0
	v_mov_b32_e32 v102, 0
	v_mov_b32_e32 v103, 0
	v_mov_b32_e32 v104, 0
	v_mov_b32_e32 v105, 0
	v_mov_b32_e32 v106, 0
	v_mov_b32_e32 v107, 0
	v_mov_b32_e32 v108, 0
	v_mov_b32_e32 v109, 0
	v_mov_b32_e32 v110, 0
	v_mov_b32_e32 v111, 0
	v_mov_b32_e32 v112, 0
	v_mov_b32_e32 v113, 0
	v_mov_b32_e32 v114, 0
	v_mov_b32_e32 v115, 0
	v_mov_b32_e32 v116, 0
	v_mov_b32_e32 v117, 0
	v_mov_b32_e32 v118, 0
	v_mov_b32_e32 v119, 0
	v_mov_b32_e32 v120, 0
	v_mov_b32_e32 v121, 0
	v_mov_b32_e32 v122, 0
	v_mov_b32_e32 v123, 0
	v_mov_b32_e32 v124, 0
	v_mov_b32_e32 v125, 0
	v_mov_b32_e32 v126, 0
	v_mov_b32_e32 v127, 0
	s_mov_b32 s63, 0
.Lg2_ff1_loop16:
	s_waitcnt vmcnt(0)
	s_barrier
	s_add_u32 s56, s56, 0x80
	s_addc_u32 s57, s57, 0
	s_add_u32 s58, s58, 0x800
	s_addc_u32 s59, s59, 0
	s_add_u32 m0, s62, 0x8800
	s_add_u32 s4, s56, 0x0
	s_addc_u32 s5, s57, 0
	global_load_lds_dwordx4 v162, s[4:5]
	s_add_u32 m0, s62, 0x9800
	s_add_u32 s4, s56, 0x10000
	s_addc_u32 s5, s57, 0
	global_load_lds_dwordx4 v162, s[4:5]
	s_add_u32 m0, s62, 0xa800
	s_add_u32 s4, s56, 0x20000
	s_addc_u32 s5, s57, 0
	global_load_lds_dwordx4 v162, s[4:5]
	s_add_u32 m0, s62, 0xb800
	s_add_u32 s4, s56, 0x30000
	s_addc_u32 s5, s57, 0
	global_load_lds_dwordx4 v162, s[4:5]
	s_add_u32 m0, s62, 0xc800
	s_add_u32 s4, s56, 0x40000
	s_addc_u32 s5, s57, 0
	global_load_lds_dwordx4 v162, s[4:5]
	s_add_u32 m0, s62, 0xd800
	s_add_u32 s4, s56, 0x50000
	s_addc_u32 s5, s57, 0
	global_load_lds_dwordx4 v162, s[4:5]
	s_add_u32 m0, s62, 0xe800
	s_add_u32 s4, s56, 0x60000
	s_addc_u32 s5, s57, 0
	global_load_lds_dwordx4 v162, s[4:5]
	s_add_u32 m0, s62, 0xf800
	s_add_u32 s4, s56, 0x70000
	s_addc_u32 s5, s57, 0
	global_load_lds_dwordx4 v162, s[4:5]
	global_load_dwordx4 v[200:203], v160, s[58:59] offset:0
	global_load_dwordx4 v[204:207], v160, s[58:59] offset:1024
	global_load_dwordx4 v[208:211], v161, s[58:59] offset:0
	global_load_dwordx4 v[240:243], v161, s[58:59] offset:1024
	ds_read_b128 v[136:139], v156 offset:0
	ds_read_b128 v[140:143], v156 offset:2048
	ds_read_b128 v[144:147], v156 offset:4096
	ds_read_b128 v[148:151], v156 offset:6144
	ds_read_b128 v[164:167], v156 offset:8192
	ds_read_b128 v[168:171], v156 offset:10240
	ds_read_b128 v[172:175], v156 offset:12288
	ds_read_b128 v[176:179], v156 offset:14336
	s_waitcnt lgkmcnt(4)
	v_mfma_f32_16x16x32_bf16 v[0:3], v[184:187], v[136:139], v[0:3]
	v_mfma_f32_16x16x32_bf16 v[4:7], v[192:195], v[136:139], v[4:7]
	v_mfma_f32_16x16x32_bf16 v[8:11], v[184:187], v[140:143], v[8:11]
	v_mfma_f32_16x16x32_bf16 v[12:15], v[192:195], v[140:143], v[12:15]
	v_mfma_f32_16x16x32_bf16 v[16:19], v[184:187], v[144:147], v[16:19]
	v_mfma_f32_16x16x32_bf16 v[20:23], v[192:195], v[144:147], v[20:23]
	v_mfma_f32_16x16x32_bf16 v[24:27], v[184:187], v[148:151], v[24:27]
	v_mfma_f32_16x16x32_bf16 v[28:31], v[192:195], v[148:151], v[28:31]
	ds_read_b128 v[136:139], v156 offset:16384
	ds_read_b128 v[140:143], v156 offset:18432
	ds_read_b128 v[144:147], v156 offset:20480
	ds_read_b128 v[148:151], v156 offset:22528
	s_waitcnt lgkmcnt(4)
	v_mfma_f32_16x16x32_bf16 v[32:35], v[184:187], v[164:167], v[32:35]
	v_mfma_f32_16x16x32_bf16 v[36:39], v[192:195], v[164:167], v[36:39]
	v_mfma_f32_16x16x32_bf16 v[40:43], v[184:187], v[168:171], v[40:43]
	v_mfma_f32_16x16x32_bf16 v[44:47], v[192:195], v[168:171], v[44:47]
	v_mfma_f32_16x16x32_bf16 v[48:51], v[184:187], v[172:175], v[48:51]
	v_mfma_f32_16x16x32_bf16 v[52:55], v[192:195], v[172:175], v[52:55]
	v_mfma_f32_16x16x32_bf16 v[56:59], v[184:187], v[176:179], v[56:59]
	v_mfma_f32_16x16x32_bf16 v[60:63], v[192:195], v[176:179], v[60:63]
	ds_read_b128 v[164:167], v156 offset:24576
	ds_read_b128 v[168:171], v156 offset:26624
	ds_read_b128 v[172:175], v156 offset:28672
	ds_read_b128 v[176:179], v156 offset:30720
	s_waitcnt lgkmcnt(4)
	v_mfma_f32_16x16x32_bf16 v[64:67], v[184:187], v[136:139], v[64:67]
	v_mfma_f32_16x16x32_bf16 v[68:71], v[192:195], v[136:139], v[68:71]
	v_mfma_f32_16x16x32_bf16 v[72:75], v[184:187], v[140:143], v[72:75]
	v_mfma_f32_16x16x32_bf16 v[76:79], v[192:195], v[140:143], v[76:79]
	v_mfma_f32_16x16x32_bf16 v[80:83], v[184:187], v[144:147], v[80:83]
	v_mfma_f32_16x16x32_bf16 v[84:87], v[192:195], v[144:147], v[84:87]
	v_mfma_f32_16x16x32_bf16 v[88:91], v[184:187], v[148:151], v[88:91]
	v_mfma_f32_16x16x32_bf16 v[92:95], v[192:195], v[148:151], v[92:95]
	ds_read_b128 v[136:139], v157 offset:0
	ds_read_b128 v[140:143], v157 offset:2048
	ds_read_b128 v[144:147], v157 offset:4096
	ds_read_b128 v[148:151], v157 offset:6144
	s_waitcnt lgkmcnt(4)
	v_mfma_f32_16x16x32_bf16 v[96:99], v[184:187], v[164:167], v[96:99]
	v_mfma_f32_16x16x32_bf16 v[100:103], v[192:195], v[164:167], v[100:103]
	v_mfma_f32_16x16x32_bf16 v[104:107], v[184:187], v[168:171], v[104:107]
	v_mfma_f32_16x16x32_bf16 v[108:111], v[192:195], v[168:171], v[108:111]
	v_mfma_f32_16x16x32_bf16 v[112:115], v[184:187], v[172:175], v[112:115]
	v_mfma_f32_16x16x32_bf16 v[116:119], v[192:195], v[172:175], v[116:119]
	v_mfma_f32_16x16x32_bf16 v[120:123], v[184:187], v[176:179], v[120:123]
	v_mfma_f32_16x16x32_bf16 v[124:127], v[192:195], v[176:179], v[124:127]
	ds_read_b128 v[164:167], v157 offset:8192
	ds_read_b128 v[168:171], v157 offset:10240
	ds_read_b128 v[172:175], v157 offset:12288
	ds_read_b128 v[176:179], v157 offset:14336
	s_waitcnt lgkmcnt(4)
	v_mfma_f32_16x16x32_bf16 v[0:3], v[188:191], v[136:139], v[0:3]
	v_mfma_f32_16x16x32_bf16 v[4:7], v[196:199], v[136:139], v[4:7]
	v_mfma_f32_16x16x32_bf16 v[8:11], v[188:191], v[140:143], v[8:11]
	v_mfma_f32_16x16x32_bf16 v[12:15], v[196:199], v[140:143], v[12:15]
	v_mfma_f32_16x16x32_bf16 v[16:19], v[188:191], v[144:147], v[16:19]
	v_mfma_f32_16x16x32_bf16 v[20:23], v[196:199], v[144:147], v[20:23]
	v_mfma_f32_16x16x32_bf16 v[24:27], v[188:191], v[148:151], v[24:27]
	v_mfma_f32_16x16x32_bf16 v[28:31], v[196:199], v[148:151], v[28:31]
	ds_read_b128 v[136:139], v157 offset:16384
	ds_read_b128 v[140:143], v157 offset:18432
	ds_read_b128 v[144:147], v157 offset:20480
	ds_read_b128 v[148:151], v157 offset:22528
	s_waitcnt lgkmcnt(4)
	v_mfma_f32_16x16x32_bf16 v[32:35], v[188:191], v[164:167], v[32:35]
	v_mfma_f32_16x16x32_bf16 v[36:39], v[196:199], v[164:167], v[36:39]
	v_mfma_f32_16x16x32_bf16 v[40:43], v[188:191], v[168:171], v[40:43]
	v_mfma_f32_16x16x32_bf16 v[44:47], v[196:199], v[168:171], v[44:47]
	v_mfma_f32_16x16x32_bf16 v[48:51], v[188:191], v[172:175], v[48:51]
	v_mfma_f32_16x16x32_bf16 v[52:55], v[196:199], v[172:175], v[52:55]
	v_mfma_f32_16x16x32_bf16 v[56:59], v[188:191], v[176:179], v[56:59]
	v_mfma_f32_16x16x32_bf16 v[60:63], v[196:199], v[176:179], v[60:63]
	ds_read_b128 v[164:167], v157 offset:24576
	ds_read_b128 v[168:171], v157 offset:26624
	ds_read_b128 v[172:175], v157 offset:28672
	ds_read_b128 v[176:179], v157 offset:30720
	s_waitcnt lgkmcnt(4)
	v_mfma_f32_16x16x32_bf16 v[64:67], v[188:191], v[136:139], v[64:67]
	v_mfma_f32_16x16x32_bf16 v[68:71], v[196:199], v[136:139], v[68:71]
	v_mfma_f32_16x16x32_bf16 v[72:75], v[188:191], v[140:143], v[72:75]
	v_mfma_f32_16x16x32_bf16 v[76:79], v[196:199], v[140:143], v[76:79]
	v_mfma_f32_16x16x32_bf16 v[80:83], v[188:191], v[144:147], v[80:83]
	v_mfma_f32_16x16x32_bf16 v[84:87], v[196:199], v[144:147], v[84:87]
	v_mfma_f32_16x16x32_bf16 v[88:91], v[188:191], v[148:151], v[88:91]
	v_mfma_f32_16x16x32_bf16 v[92:95], v[196:199], v[148:151], v[92:95]
	s_waitcnt lgkmcnt(0)
	v_mfma_f32_16x16x32_bf16 v[96:99], v[188:191], v[164:167], v[96:99]
	v_mfma_f32_16x16x32_bf16 v[100:103], v[196:199], v[164:167], v[100:103]
	v_mfma_f32_16x16x32_bf16 v[104:107], v[188:191], v[168:171], v[104:107]
	v_mfma_f32_16x16x32_bf16 v[108:111], v[196:199], v[168:171], v[108:111]
	v_mfma_f32_16x16x32_bf16 v[112:115], v[188:191], v[172:175], v[112:115]
	v_mfma_f32_16x16x32_bf16 v[116:119], v[196:199], v[172:175], v[116:119]
	v_mfma_f32_16x16x32_bf16 v[120:123], v[188:191], v[176:179], v[120:123]
	v_mfma_f32_16x16x32_bf16 v[124:127], v[196:199], v[176:179], v[124:127]
	s_waitcnt vmcnt(0)
	s_barrier
	s_cmp_ge_u32 s63, 14
	s_cbranch_scc1 .Lg2_ff1_noissue16
	s_add_u32 s56, s56, 0x80
	s_addc_u32 s57, s57, 0
	s_add_u32 s58, s58, 0x800
	s_addc_u32 s59, s59, 0
	s_add_u32 m0, s62, 0x0
	s_add_u32 s4, s56, 0x0
	s_addc_u32 s5, s57, 0
	global_load_lds_dwordx4 v162, s[4:5]
	s_add_u32 m0, s62, 0x1000
	s_add_u32 s4, s56, 0x10000
	s_addc_u32 s5, s57, 0
	global_load_lds_dwordx4 v162, s[4:5]
	s_add_u32 m0, s62, 0x2000
	s_add_u32 s4, s56, 0x20000
	s_addc_u32 s5, s57, 0
	global_load_lds_dwordx4 v162, s[4:5]
	s_add_u32 m0, s62, 0x3000
	s_add_u32 s4, s56, 0x30000
	s_addc_u32 s5, s57, 0
	global_load_lds_dwordx4 v162, s[4:5]
	s_add_u32 m0, s62, 0x4000
	s_add_u32 s4, s56, 0x40000
	s_addc_u32 s5, s57, 0
	global_load_lds_dwordx4 v162, s[4:5]
	s_add_u32 m0, s62, 0x5000
	s_add_u32 s4, s56, 0x50000
	s_addc_u32 s5, s57, 0
	global_load_lds_dwordx4 v162, s[4:5]
	s_add_u32 m0, s62, 0x6000
	s_add_u32 s4, s56, 0x60000
	s_addc_u32 s5, s57, 0
	global_load_lds_dwordx4 v162, s[4:5]
	s_add_u32 m0, s62, 0x7000
	s_add_u32 s4, s56, 0x70000
	s_addc_u32 s5, s57, 0
	global_load_lds_dwordx4 v162, s[4:5]
	global_load_dwordx4 v[184:187], v160, s[58:59] offset:0
	global_load_dwordx4 v[188:191], v160, s[58:59] offset:1024
	global_load_dwordx4 v[192:195], v161, s[58:59] offset:0
	global_load_dwordx4 v[196:199], v161, s[58:59] offset:1024

.Lg2_ff1_episel:
.Lg2_ff1_epiP:
	s_nop 7
	s_nop 7
	s_barrier
	v_max_f32_e32 v0, 0, v0
	v_max_f32_e32 v1, 0, v1
	v_max_f32_e32 v2, 0, v2
	v_max_f32_e32 v3, 0, v3
	v_pk_mul_f32 v[0:1], v[0:1], v[0:1]
	v_pk_mul_f32 v[2:3], v[2:3], v[2:3]
	v_cvt_pk_bf16_f32 v0, v0, v1
	v_cvt_pk_bf16_f32 v1, v2, v3
	ds_write_b64 v212, v[0:1] offset:0
	v_max_f32_e32 v4, 0, v4
	v_max_f32_e32 v5, 0, v5
	v_max_f32_e32 v6, 0, v6
	v_max_f32_e32 v7, 0, v7
	v_pk_mul_f32 v[4:5], v[4:5], v[4:5]
	v_pk_mul_f32 v[6:7], v[6:7], v[6:7]
	v_cvt_pk_bf16_f32 v4, v4, v5
	v_cvt_pk_bf16_f32 v5, v6, v7
	ds_write_b64 v213, v[4:5] offset:0
	v_max_f32_e32 v8, 0, v8
	v_max_f32_e32 v9, 0, v9
	v_max_f32_e32 v10, 0, v10
	v_max_f32_e32 v11, 0, v11
	v_pk_mul_f32 v[8:9], v[8:9], v[8:9]
	v_pk_mul_f32 v[10:11], v[10:11], v[10:11]
	v_cvt_pk_bf16_f32 v8, v8, v9
	v_cvt_pk_bf16_f32 v9, v10, v11
	ds_write_b64 v212, v[8:9] offset:4096
	v_max_f32_e32 v12, 0, v12
	v_max_f32_e32 v13, 0, v13
	v_max_f32_e32 v14, 0, v14
	v_max_f32_e32 v15, 0, v15
	v_pk_mul_f32 v[12:13], v[12:13], v[12:13]
	v_pk_mul_f32 v[14:15], v[14:15], v[14:15]
	v_cvt_pk_bf16_f32 v12, v12, v13
	v_cvt_pk_bf16_f32 v13, v14, v15
	ds_write_b64 v213, v[12:13] offset:4096
	v_max_f32_e32 v16, 0, v16
	v_max_f32_e32 v17, 0, v17
	v_max_f32_e32 v18, 0, v18
	v_max_f32_e32 v19, 0, v19
	v_pk_mul_f32 v[16:17], v[16:17], v[16:17]
	v_pk_mul_f32 v[18:19], v[18:19], v[18:19]
	v_cvt_pk_bf16_f32 v16, v16, v17
	v_cvt_pk_bf16_f32 v17, v18, v19
	ds_write_b64 v212, v[16:17] offset:8192
	v_max_f32_e32 v20, 0, v20
	v_max_f32_e32 v21, 0, v21
	v_max_f32_e32 v22, 0, v22
	v_max_f32_e32 v23, 0, v23
	v_pk_mul_f32 v[20:21], v[20:21], v[20:21]
	v_pk_mul_f32 v[22:23], v[22:23], v[22:23]
	v_cvt_pk_bf16_f32 v20, v20, v21
	v_cvt_pk_bf16_f32 v21, v22, v23
	ds_write_b64 v213, v[20:21] offset:8192
	v_max_f32_e32 v24, 0, v24
	v_max_f32_e32 v25, 0, v25
	v_max_f32_e32 v26, 0, v26
	v_max_f32_e32 v27, 0, v27
	v_pk_mul_f32 v[24:25], v[24:25], v[24:25]
	v_pk_mul_f32 v[26:27], v[26:27], v[26:27]
	v_cvt_pk_bf16_f32 v24, v24, v25
	v_cvt_pk_bf16_f32 v25, v26, v27
	ds_write_b64 v212, v[24:25] offset:12288
	v_max_f32_e32 v28, 0, v28
	v_max_f32_e32 v29, 0, v29
	v_max_f32_e32 v30, 0, v30
	v_max_f32_e32 v31, 0, v31
	v_pk_mul_f32 v[28:29], v[28:29], v[28:29]
	v_pk_mul_f32 v[30:31], v[30:31], v[30:31]
	v_cvt_pk_bf16_f32 v28, v28, v29
	v_cvt_pk_bf16_f32 v29, v30, v31
	ds_write_b64 v213, v[28:29] offset:12288
	v_max_f32_e32 v32, 0, v32
	v_max_f32_e32 v33, 0, v33
	v_max_f32_e32 v34, 0, v34
	v_max_f32_e32 v35, 0, v35
	v_pk_mul_f32 v[32:33], v[32:33], v[32:33]
	v_pk_mul_f32 v[34:35], v[34:35], v[34:35]
	v_cvt_pk_bf16_f32 v32, v32, v33
	v_cvt_pk_bf16_f32 v33, v34, v35
	ds_write_b64 v212, v[32:33] offset:16384
	v_max_f32_e32 v36, 0, v36
	v_max_f32_e32 v37, 0, v37
	v_max_f32_e32 v38, 0, v38
	v_max_f32_e32 v39, 0, v39
	v_pk_mul_f32 v[36:37], v[36:37], v[36:37]
	v_pk_mul_f32 v[38:39], v[38:39], v[38:39]
	v_cvt_pk_bf16_f32 v36, v36, v37
	v_cvt_pk_bf16_f32 v37, v38, v39
	ds_write_b64 v213, v[36:37] offset:16384
	v_max_f32_e32 v40, 0, v40
	v_max_f32_e32 v41, 0, v41
	v_max_f32_e32 v42, 0, v42
	v_max_f32_e32 v43, 0, v43
	v_pk_mul_f32 v[40:41], v[40:41], v[40:41]
	v_pk_mul_f32 v[42:43], v[42:43], v[42:43]
	v_cvt_pk_bf16_f32 v40, v40, v41
	v_cvt_pk_bf16_f32 v41, v42, v43
	ds_write_b64 v212, v[40:41] offset:20480
	v_max_f32_e32 v44, 0, v44
	v_max_f32_e32 v45, 0, v45
	v_max_f32_e32 v46, 0, v46
	v_max_f32_e32 v47, 0, v47
	v_pk_mul_f32 v[44:45], v[44:45], v[44:45]
	v_pk_mul_f32 v[46:47], v[46:47], v[46:47]
	v_cvt_pk_bf16_f32 v44, v44, v45
	v_cvt_pk_bf16_f32 v45, v46, v47
	ds_write_b64 v213, v[44:45] offset:20480
	v_max_f32_e32 v48, 0, v48
	v_max_f32_e32 v49, 0, v49
	v_max_f32_e32 v50, 0, v50
	v_max_f32_e32 v51, 0, v51
	v_pk_mul_f32 v[48:49], v[48:49], v[48:49]
	v_pk_mul_f32 v[50:51], v[50:51], v[50:51]
	v_cvt_pk_bf16_f32 v48, v48, v49
	v_cvt_pk_bf16_f32 v49, v50, v51
	ds_write_b64 v212, v[48:49] offset:24576
	v_max_f32_e32 v52, 0, v52
	v_max_f32_e32 v53, 0, v53
	v_max_f32_e32 v54, 0, v54
	v_max_f32_e32 v55, 0, v55
	v_pk_mul_f32 v[52:53], v[52:53], v[52:53]
	v_pk_mul_f32 v[54:55], v[54:55], v[54:55]
	v_cvt_pk_bf16_f32 v52, v52, v53
	v_cvt_pk_bf16_f32 v53, v54, v55
	ds_write_b64 v213, v[52:53] offset:24576
	v_max_f32_e32 v56, 0, v56
	v_max_f32_e32 v57, 0, v57
	v_max_f32_e32 v58, 0, v58
	v_max_f32_e32 v59, 0, v59
	v_pk_mul_f32 v[56:57], v[56:57], v[56:57]
	v_pk_mul_f32 v[58:59], v[58:59], v[58:59]
	v_cvt_pk_bf16_f32 v56, v56, v57
	v_cvt_pk_bf16_f32 v57, v58, v59
	ds_write_b64 v212, v[56:57] offset:28672
	v_max_f32_e32 v60, 0, v60
	v_max_f32_e32 v61, 0, v61
	v_max_f32_e32 v62, 0, v62
	v_max_f32_e32 v63, 0, v63
	v_pk_mul_f32 v[60:61], v[60:61], v[60:61]
	v_pk_mul_f32 v[62:63], v[62:63], v[62:63]
	v_cvt_pk_bf16_f32 v60, v60, v61
	v_cvt_pk_bf16_f32 v61, v62, v63
	ds_write_b64 v213, v[60:61] offset:28672
	v_max_f32_e32 v64, 0, v64
	v_max_f32_e32 v65, 0, v65
	v_max_f32_e32 v66, 0, v66
	v_max_f32_e32 v67, 0, v67
	v_pk_mul_f32 v[64:65], v[64:65], v[64:65]
	v_pk_mul_f32 v[66:67], v[66:67], v[66:67]
	v_cvt_pk_bf16_f32 v64, v64, v65
	v_cvt_pk_bf16_f32 v65, v66, v67
	ds_write_b64 v253, v[64:65] offset:0
	v_max_f32_e32 v68, 0, v68
	v_max_f32_e32 v69, 0, v69
	v_max_f32_e32 v70, 0, v70
	v_max_f32_e32 v71, 0, v71
	v_pk_mul_f32 v[68:69], v[68:69], v[68:69]
	v_pk_mul_f32 v[70:71], v[70:71], v[70:71]
	v_cvt_pk_bf16_f32 v68, v68, v69
	v_cvt_pk_bf16_f32 v69, v70, v71
	ds_write_b64 v254, v[68:69] offset:0
	v_max_f32_e32 v72, 0, v72
	v_max_f32_e32 v73, 0, v73
	v_max_f32_e32 v74, 0, v74
	v_max_f32_e32 v75, 0, v75
	v_pk_mul_f32 v[72:73], v[72:73], v[72:73]
	v_pk_mul_f32 v[74:75], v[74:75], v[74:75]
	v_cvt_pk_bf16_f32 v72, v72, v73
	v_cvt_pk_bf16_f32 v73, v74, v75
	ds_write_b64 v253, v[72:73] offset:4096
	v_max_f32_e32 v76, 0, v76
	v_max_f32_e32 v77, 0, v77
	v_max_f32_e32 v78, 0, v78
	v_max_f32_e32 v79, 0, v79
	v_pk_mul_f32 v[76:77], v[76:77], v[76:77]
	v_pk_mul_f32 v[78:79], v[78:79], v[78:79]
	v_cvt_pk_bf16_f32 v76, v76, v77
	v_cvt_pk_bf16_f32 v77, v78, v79
	ds_write_b64 v254, v[76:77] offset:4096
	v_max_f32_e32 v80, 0, v80
	v_max_f32_e32 v81, 0, v81
	v_max_f32_e32 v82, 0, v82
	v_max_f32_e32 v83, 0, v83
	v_pk_mul_f32 v[80:81], v[80:81], v[80:81]
	v_pk_mul_f32 v[82:83], v[82:83], v[82:83]
	v_cvt_pk_bf16_f32 v80, v80, v81
	v_cvt_pk_bf16_f32 v81, v82, v83
	ds_write_b64 v253, v[80:81] offset:8192
	v_max_f32_e32 v84, 0, v84
	v_max_f32_e32 v85, 0, v85
	v_max_f32_e32 v86, 0, v86
	v_max_f32_e32 v87, 0, v87
	v_pk_mul_f32 v[84:85], v[84:85], v[84:85]
	v_pk_mul_f32 v[86:87], v[86:87], v[86:87]
	v_cvt_pk_bf16_f32 v84, v84, v85
	v_cvt_pk_bf16_f32 v85, v86, v87
	ds_write_b64 v254, v[84:85] offset:8192
	v_max_f32_e32 v88, 0, v88
	v_max_f32_e32 v89, 0, v89
	v_max_f32_e32 v90, 0, v90
	v_max_f32_e32 v91, 0, v91
	v_pk_mul_f32 v[88:89], v[88:89], v[88:89]
	v_pk_mul_f32 v[90:91], v[90:91], v[90:91]
	v_cvt_pk_bf16_f32 v88, v88, v89
	v_cvt_pk_bf16_f32 v89, v90, v91
	ds_write_b64 v253, v[88:89] offset:12288
	v_max_f32_e32 v92, 0, v92
	v_max_f32_e32 v93, 0, v93
	v_max_f32_e32 v94, 0, v94
	v_max_f32_e32 v95, 0, v95
	v_pk_mul_f32 v[92:93], v[92:93], v[92:93]
	v_pk_mul_f32 v[94:95], v[94:95], v[94:95]
	v_cvt_pk_bf16_f32 v92, v92, v93
	v_cvt_pk_bf16_f32 v93, v94, v95
	ds_write_b64 v254, v[92:93] offset:12288
	v_max_f32_e32 v96, 0, v96
	v_max_f32_e32 v97, 0, v97
	v_max_f32_e32 v98, 0, v98
	v_max_f32_e32 v99, 0, v99
	v_pk_mul_f32 v[96:97], v[96:97], v[96:97]
	v_pk_mul_f32 v[98:99], v[98:99], v[98:99]
	v_cvt_pk_bf16_f32 v96, v96, v97
	v_cvt_pk_bf16_f32 v97, v98, v99
	ds_write_b64 v253, v[96:97] offset:16384
	v_max_f32_e32 v100, 0, v100
	v_max_f32_e32 v101, 0, v101
	v_max_f32_e32 v102, 0, v102
	v_max_f32_e32 v103, 0, v103
	v_pk_mul_f32 v[100:101], v[100:101], v[100:101]
	v_pk_mul_f32 v[102:103], v[102:103], v[102:103]
	v_cvt_pk_bf16_f32 v100, v100, v101
	v_cvt_pk_bf16_f32 v101, v102, v103
	ds_write_b64 v254, v[100:101] offset:16384
	v_max_f32_e32 v104, 0, v104
	v_max_f32_e32 v105, 0, v105
	v_max_f32_e32 v106, 0, v106
	v_max_f32_e32 v107, 0, v107
	v_pk_mul_f32 v[104:105], v[104:105], v[104:105]
	v_pk_mul_f32 v[106:107], v[106:107], v[106:107]
	v_cvt_pk_bf16_f32 v104, v104, v105
	v_cvt_pk_bf16_f32 v105, v106, v107
	ds_write_b64 v253, v[104:105] offset:20480
	v_max_f32_e32 v108, 0, v108
	v_max_f32_e32 v109, 0, v109
	v_max_f32_e32 v110, 0, v110
	v_max_f32_e32 v111, 0, v111
	v_pk_mul_f32 v[108:109], v[108:109], v[108:109]
	v_pk_mul_f32 v[110:111], v[110:111], v[110:111]
	v_cvt_pk_bf16_f32 v108, v108, v109
	v_cvt_pk_bf16_f32 v109, v110, v111
	ds_write_b64 v254, v[108:109] offset:20480
	v_max_f32_e32 v112, 0, v112
	v_max_f32_e32 v113, 0, v113
	v_max_f32_e32 v114, 0, v114
	v_max_f32_e32 v115, 0, v115
	v_pk_mul_f32 v[112:113], v[112:113], v[112:113]
	v_pk_mul_f32 v[114:115], v[114:115], v[114:115]
	v_cvt_pk_bf16_f32 v112, v112, v113
	v_cvt_pk_bf16_f32 v113, v114, v115
	ds_write_b64 v253, v[112:113] offset:24576
	v_max_f32_e32 v116, 0, v116
	v_max_f32_e32 v117, 0, v117
	v_max_f32_e32 v118, 0, v118
	v_max_f32_e32 v119, 0, v119
	v_pk_mul_f32 v[116:117], v[116:117], v[116:117]
	v_pk_mul_f32 v[118:119], v[118:119], v[118:119]
	v_cvt_pk_bf16_f32 v116, v116, v117
	v_cvt_pk_bf16_f32 v117, v118, v119
	ds_write_b64 v254, v[116:117] offset:24576
	v_max_f32_e32 v120, 0, v120
	v_max_f32_e32 v121, 0, v121
	v_max_f32_e32 v122, 0, v122
	v_max_f32_e32 v123, 0, v123
	v_pk_mul_f32 v[120:121], v[120:121], v[120:121]
	v_pk_mul_f32 v[122:123], v[122:123], v[122:123]
	v_cvt_pk_bf16_f32 v120, v120, v121
	v_cvt_pk_bf16_f32 v121, v122, v123
	ds_write_b64 v253, v[120:121] offset:28672
	v_max_f32_e32 v124, 0, v124
	v_max_f32_e32 v125, 0, v125
	v_max_f32_e32 v126, 0, v126
	v_max_f32_e32 v127, 0, v127
	v_pk_mul_f32 v[124:125], v[124:125], v[124:125]
	v_pk_mul_f32 v[126:127], v[126:127], v[126:127]
	v_cvt_pk_bf16_f32 v124, v124, v125
	v_cvt_pk_bf16_f32 v125, v126, v127
	ds_write_b64 v254, v[124:125] offset:28672
	s_cmp_eq_u32 s65, 0
	s_cbranch_scc1 .Lg2_ff1_st_lastP
	v_max_f32_e32 v128, 0, v128
	v_max_f32_e32 v129, 0, v129
	v_max_f32_e32 v130, 0, v130
	v_max_f32_e32 v131, 0, v131
	v_pk_mul_f32 v[128:129], v[128:129], v[128:129]
	v_pk_mul_f32 v[130:131], v[130:131], v[130:131]
	v_cvt_pk_bf16_f32 v128, v128, v129
	v_cvt_pk_bf16_f32 v129, v130, v131
	ds_write_b64 v253, v[128:129] offset:32768
	v_max_f32_e32 v132, 0, v132
	v_max_f32_e32 v133, 0, v133
	v_max_f32_e32 v134, 0, v134
	v_max_f32_e32 v135, 0, v135
	v_pk_mul_f32 v[132:133], v[132:133], v[132:133]
	v_pk_mul_f32 v[134:135], v[134:135], v[134:135]
	v_cvt_pk_bf16_f32 v132, v132, v133
	v_cvt_pk_bf16_f32 v133, v134, v135
	ds_write_b64 v254, v[132:133] offset:32768

.Lg2_ff1_rd_lastaP:
	s_waitcnt lgkmcnt(15)
	global_store_dwordx4 v252, v[0:3], s[60:61]
	s_add_u32 s60, s60, 0x20000
	s_addc_u32 s61, s61, 0
	s_waitcnt lgkmcnt(14)
	global_store_dwordx4 v252, v[4:7], s[60:61]
	s_add_u32 s60, s60, 0x20000
	s_addc_u32 s61, s61, 0
	s_waitcnt lgkmcnt(13)
	global_store_dwordx4 v252, v[8:11], s[60:61]
	s_add_u32 s60, s60, 0x20000
	s_addc_u32 s61, s61, 0
	s_waitcnt lgkmcnt(12)
	global_store_dwordx4 v252, v[12:15], s[60:61]
	s_add_u32 s60, s60, 0x20000
	s_addc_u32 s61, s61, 0
	s_waitcnt lgkmcnt(11)
	global_store_dwordx4 v252, v[16:19], s[60:61]
	s_add_u32 s60, s60, 0x20000
	s_addc_u32 s61, s61, 0
	s_waitcnt lgkmcnt(10)
	global_store_dwordx4 v252, v[20:23], s[60:61]
	s_add_u32 s60, s60, 0x20000
	s_addc_u32 s61, s61, 0
	s_waitcnt lgkmcnt(9)
	global_store_dwordx4 v252, v[24:27], s[60:61]
	s_add_u32 s60, s60, 0x20000
	s_addc_u32 s61, s61, 0
	s_waitcnt lgkmcnt(8)
	global_store_dwordx4 v252, v[28:31], s[60:61]
	s_add_u32 s60, s60, 0x20000
	s_addc_u32 s61, s61, 0
	s_waitcnt lgkmcnt(7)
	global_store_dwordx4 v252, v[32:35], s[60:61]
	s_add_u32 s60, s60, 0x20000
	s_addc_u32 s61, s61, 0
	s_waitcnt lgkmcnt(6)
	global_store_dwordx4 v252, v[36:39], s[60:61]
	s_add_u32 s60, s60, 0x20000
	s_addc_u32 s61, s61, 0
	s_waitcnt lgkmcnt(5)
	global_store_dwordx4 v252, v[40:43], s[60:61]
	s_add_u32 s60, s60, 0x20000
	s_addc_u32 s61, s61, 0
	s_waitcnt lgkmcnt(4)
	global_store_dwordx4 v252, v[44:47], s[60:61]
	s_add_u32 s60, s60, 0x20000
	s_addc_u32 s61, s61, 0
	s_waitcnt lgkmcnt(3)
	global_store_dwordx4 v252, v[48:51], s[60:61]
	s_add_u32 s60, s60, 0x20000
	s_addc_u32 s61, s61, 0
	s_waitcnt lgkmcnt(2)
	global_store_dwordx4 v252, v[52:55], s[60:61]
	s_add_u32 s60, s60, 0x20000
	s_addc_u32 s61, s61, 0
	s_waitcnt lgkmcnt(1)
	global_store_dwordx4 v252, v[56:59], s[60:61]
	s_add_u32 s60, s60, 0x20000
	s_addc_u32 s61, s61, 0
	s_waitcnt lgkmcnt(0)
	global_store_dwordx4 v252, v[60:63], s[60:61]
	s_add_u32 s60, s60, 0x20000
	s_addc_u32 s61, s61, 0
	s_cmp_eq_u32 s65, 0
	s_cbranch_scc1 .Lg2_ff1_rd_lastP
	s_waitcnt lgkmcnt(0)
	global_store_dwordx4 v252, v[64:67], s[60:61]
	s_add_u32 s60, s60, 0x20000
	s_addc_u32 s61, s61, 0

.Lg2_out_tile:
	s_lshl_b32 s0, s64, 3
	s_add_i32 s38, s0, s68
	s_mov_b32 s69, s42
	s_mov_b32 s65, s43
	s_lshl_b32 s0, s38, 7
	s_mul_i32 s2, s69, 0x800
	s_mul_hi_u32 s3, s69, 0x800
	s_add_u32 s56, s26, s2
	s_addc_u32 s57, s27, s3
	s_add_u32 s56, s56, 0x13240000
	s_addc_u32 s57, s57, 0
	s_mul_i32 s2, s0, 0x800
	s_mul_hi_u32 s3, s0, 0x800
	s_add_u32 s58, s26, s2
	s_addc_u32 s59, s27, s3
	s_add_u32 s58, s58, 0xfd40000
	s_addc_u32 s59, s59, 0
	s_mul_i32 s2, s69, 0x800
	s_mul_hi_u32 s3, s69, 0x800
	s_lshl_b32 s0, s0, 1
	s_add_u32 s2, s2, s0
	s_addc_u32 s3, s3, 0
	s_add_u32 s60, s26, s2
	s_addc_u32 s61, s27, s3
	s_add_u32 s60, s60, 0x11140000
	s_addc_u32 s61, s61, 0
	s_cmp_eq_u32 s65, 0
	s_cbranch_scc1 .Lg2_out_k16
	s_add_u32 m0, s62, 0x0
	s_add_u32 s4, s56, 0x0
	s_addc_u32 s5, s57, 0
	global_load_lds_dwordx4 v162, s[4:5]
	s_add_u32 m0, s62, 0x1000
	s_add_u32 s4, s56, 0x10000
	s_addc_u32 s5, s57, 0
	global_load_lds_dwordx4 v162, s[4:5]
	s_add_u32 m0, s62, 0x2000
	s_add_u32 s4, s56, 0x20000
	s_addc_u32 s5, s57, 0
	global_load_lds_dwordx4 v162, s[4:5]
	s_add_u32 m0, s62, 0x3000
	s_add_u32 s4, s56, 0x30000
	s_addc_u32 s5, s57, 0
	global_load_lds_dwordx4 v162, s[4:5]
	s_add_u32 m0, s62, 0x4000
	s_add_u32 s4, s56, 0x40000
	s_addc_u32 s5, s57, 0
	global_load_lds_dwordx4 v162, s[4:5]
	s_add_u32 m0, s62, 0x5000
	s_add_u32 s4, s56, 0x50000
	s_addc_u32 s5, s57, 0
	global_load_lds_dwordx4 v162, s[4:5]
	s_add_u32 m0, s62, 0x6000
	s_add_u32 s4, s56, 0x60000
	s_addc_u32 s5, s57, 0
	global_load_lds_dwordx4 v162, s[4:5]
	s_add_u32 m0, s62, 0x7000
	s_add_u32 s4, s56, 0x70000
	s_addc_u32 s5, s57, 0
	global_load_lds_dwordx4 v162, s[4:5]
	s_cmp_gt_u32 s70, 1
	s_cbranch_scc1 .Lg2_out_nodma_0
	s_add_u32 m0, s62, 0x8000
	s_add_u32 s4, s56, 0x80000
	s_addc_u32 s5, s57, 0
	global_load_lds_dwordx4 v162, s[4:5]

.Lg2_win_tile:
	s_lshl_b32 s0, s64, 3
	s_add_i32 s38, s0, s68
	s_mov_b32 s69, s42
	s_mov_b32 s65, s43
	s_lshl_b32 s0, s38, 7
	s_mul_i32 s2, s69, 0x800
	s_mul_hi_u32 s3, s69, 0x800
	s_add_u32 s56, s26, s2
	s_addc_u32 s57, s27, s3
	s_add_u32 s56, s56, 0x11140000
	s_addc_u32 s57, s57, 0
	s_mul_i32 s2, s0, 0x800
	s_mul_hi_u32 s3, s0, 0x800
	s_add_u32 s58, s26, s2
	s_addc_u32 s59, s27, s3
	s_add_u32 s58, s58, 0xeb20000
	s_addc_u32 s59, s59, 0
	s_mul_i32 s2, s69, 0x3900
	s_mul_hi_u32 s3, s69, 0x3900
	s_lshl_b32 s0, s0, 1
	s_add_u32 s2, s2, s0
	s_addc_u32 s3, s3, 0
	s_add_u32 s60, s26, s2
	s_addc_u32 s61, s27, s3
	s_add_u32 s60, s60, 0x0
	s_addc_u32 s61, s61, 0
	s_cmp_eq_u32 s65, 0
	s_cbranch_scc1 .Lg2_win_k16
	s_add_u32 m0, s62, 0x0
	s_add_u32 s4, s56, 0x0
	s_addc_u32 s5, s57, 0
	global_load_lds_dwordx4 v162, s[4:5]
	s_add_u32 m0, s62, 0x1000
	s_add_u32 s4, s56, 0x10000
	s_addc_u32 s5, s57, 0
	global_load_lds_dwordx4 v162, s[4:5]
	s_add_u32 m0, s62, 0x2000
	s_add_u32 s4, s56, 0x20000
	s_addc_u32 s5, s57, 0
	global_load_lds_dwordx4 v162, s[4:5]
	s_add_u32 m0, s62, 0x3000
	s_add_u32 s4, s56, 0x30000
	s_addc_u32 s5, s57, 0
	global_load_lds_dwordx4 v162, s[4:5]
	s_add_u32 m0, s62, 0x4000
	s_add_u32 s4, s56, 0x40000
	s_addc_u32 s5, s57, 0
	global_load_lds_dwordx4 v162, s[4:5]
	s_add_u32 m0, s62, 0x5000
	s_add_u32 s4, s56, 0x50000
	s_addc_u32 s5, s57, 0
	global_load_lds_dwordx4 v162, s[4:5]
	s_add_u32 m0, s62, 0x6000
	s_add_u32 s4, s56, 0x60000
	s_addc_u32 s5, s57, 0
	global_load_lds_dwordx4 v162, s[4:5]
	s_add_u32 m0, s62, 0x7000
	s_add_u32 s4, s56, 0x70000
	s_addc_u32 s5, s57, 0
	global_load_lds_dwordx4 v162, s[4:5]
	s_cmp_gt_u32 s70, 1
	s_cbranch_scc1 .Lg2_win_nodma_0
	s_add_u32 m0, s62, 0x8000
	s_add_u32 s4, s56, 0x80000
	s_addc_u32 s5, s57, 0
	global_load_lds_dwordx4 v162, s[4:5]

.Lg2_win_rd_lastaR:
	s_waitcnt lgkmcnt(15)
	global_store_dwordx4 v252, v[0:3], s[60:61]
	s_add_u32 s60, s60, 0x39000
	s_addc_u32 s61, s61, 0
	s_waitcnt lgkmcnt(14)
	global_store_dwordx4 v252, v[4:7], s[60:61]
	s_add_u32 s60, s60, 0x39000
	s_addc_u32 s61, s61, 0
	s_waitcnt lgkmcnt(13)
	global_store_dwordx4 v252, v[8:11], s[60:61]
	s_add_u32 s60, s60, 0x39000
	s_addc_u32 s61, s61, 0
	s_waitcnt lgkmcnt(12)
	global_store_dwordx4 v252, v[12:15], s[60:61]
	s_add_u32 s60, s60, 0x39000
	s_addc_u32 s61, s61, 0
	s_waitcnt lgkmcnt(11)
	global_store_dwordx4 v252, v[16:19], s[60:61]
	s_add_u32 s60, s60, 0x39000
	s_addc_u32 s61, s61, 0
	s_waitcnt lgkmcnt(10)
	global_store_dwordx4 v252, v[20:23], s[60:61]
	s_add_u32 s60, s60, 0x39000
	s_addc_u32 s61, s61, 0
	s_waitcnt lgkmcnt(9)
	global_store_dwordx4 v252, v[24:27], s[60:61]
	s_add_u32 s60, s60, 0x39000
	s_addc_u32 s61, s61, 0
	s_waitcnt lgkmcnt(8)
	global_store_dwordx4 v252, v[28:31], s[60:61]
	s_add_u32 s60, s60, 0x39000
	s_addc_u32 s61, s61, 0
	s_waitcnt lgkmcnt(7)
	global_store_dwordx4 v252, v[32:35], s[60:61]
	s_add_u32 s60, s60, 0x39000
	s_addc_u32 s61, s61, 0
	s_waitcnt lgkmcnt(6)
	global_store_dwordx4 v252, v[36:39], s[60:61]
	s_add_u32 s60, s60, 0x39000
	s_addc_u32 s61, s61, 0
	s_waitcnt lgkmcnt(5)
	global_store_dwordx4 v252, v[40:43], s[60:61]
	s_add_u32 s60, s60, 0x39000
	s_addc_u32 s61, s61, 0
	s_waitcnt lgkmcnt(4)
	global_store_dwordx4 v252, v[44:47], s[60:61]
	s_add_u32 s60, s60, 0x39000
	s_addc_u32 s61, s61, 0
	s_waitcnt lgkmcnt(3)
	global_store_dwordx4 v252, v[48:51], s[60:61]
	s_add_u32 s60, s60, 0x39000
	s_addc_u32 s61, s61, 0
	s_waitcnt lgkmcnt(2)
	global_store_dwordx4 v252, v[52:55], s[60:61]
	s_add_u32 s60, s60, 0x39000
	s_addc_u32 s61, s61, 0
	s_waitcnt lgkmcnt(1)
	global_store_dwordx4 v252, v[56:59], s[60:61]
	s_add_u32 s60, s60, 0x39000
	s_addc_u32 s61, s61, 0
	s_waitcnt lgkmcnt(0)
	global_store_dwordx4 v252, v[60:63], s[60:61]
	s_add_u32 s60, s60, 0x39000
	s_addc_u32 s61, s61, 0
	s_cmp_eq_u32 s65, 0
	s_cbranch_scc1 .Lg2_win_rd_lastR
	s_waitcnt lgkmcnt(0)
	global_store_dwordx4 v252, v[64:67], s[60:61]
	s_add_u32 s60, s60, 0x39000
	s_addc_u32 s61, s61, 0

.Lg2_win_next:
	s_add_i32 s64, s64, 1
	s_cmp_lt_u32 s64, 7
	s_cbranch_scc1 .Lg2_win_tile
	v_lshrrev_b32_e32 v4, 6, v163
	v_and_b32_e32 v5, 63, v163
	v_and_b32_e32 v6, 15, v5
	v_lshrrev_b32_e32 v7, 4, v5
	v_lshlrev_b32_e32 v11, 1, v4
	s_mov_b32 s2, 0x8000
	v_mul_lo_u32 v12, v11, s2
	v_lshl_add_u32 v160, v5, 4, v12
	v_add_u32_e32 v161, 0x8000, v160
	v_lshrrev_b32_e32 v12, 1, v7
	v_lshl_add_u32 v12, v11, 1, v12
	v_and_b32_e32 v13, 1, v7
	v_lshlrev_b32_e32 v13, 3, v13
	v_lshl_add_u32 v14, v6, 8, v13
	v_xor_b32_e32 v15, v12, v6
	v_lshlrev_b32_e32 v15, 4, v15
	v_add_u32_e32 v212, v14, v15
	v_add_u32_e32 v12, 2, v12
	v_xor_b32_e32 v15, v12, v6
	v_lshlrev_b32_e32 v15, 4, v15
	v_add_u32_e32 v213, v14, v15
	v_add_u32_e32 v253, 0x8000, v212
	v_add_u32_e32 v254, 0x8000, v213
	s_mov_b32 s38, 56
	s_lshl_b32 s0, s68, 5
	s_add_i32 s69, s42, s0
	s_cmp_eq_u32 s68, 7
	s_cselect_b32 s0, 1, 0
	s_and_b32 s65, s0, s43
	s_lshl_b32 s0, s38, 7
	s_mul_i32 s2, s69, 0x800
	s_mul_hi_u32 s3, s69, 0x800
	s_add_u32 s56, s26, s2
	s_addc_u32 s57, s27, s3
	s_add_u32 s56, s56, 0x11140000
	s_addc_u32 s57, s57, 0
	s_mul_i32 s2, s0, 0x800
	s_mul_hi_u32 s3, s0, 0x800
	s_add_u32 s58, s26, s2
	s_addc_u32 s59, s27, s3
	s_add_u32 s58, s58, 0xeb20000
	s_addc_u32 s59, s59, 0
	s_mul_i32 s2, s69, 0x3900
	s_mul_hi_u32 s3, s69, 0x3900
	s_lshl_b32 s0, s0, 1
	s_add_u32 s2, s2, s0
	s_addc_u32 s3, s3, 0
	s_add_u32 s60, s26, s2
	s_addc_u32 s61, s27, s3
	s_add_u32 s60, s60, 0x0
	s_addc_u32 s61, s61, 0
	s_cmp_eq_u32 s65, 0
	s_cbranch_scc1 .Lg2_win_k2
	s_add_u32 m0, s62, 0x0
	s_add_u32 s4, s56, 0x0
	s_addc_u32 s5, s57, 0
	global_load_lds_dwordx4 v162, s[4:5]
	s_cmp_gt_u32 s70, 1
	s_cbranch_scc1 .Lg2_win_nodma_3
	s_add_u32 m0, s62, 0x1000
	s_add_u32 s4, s56, 0x10000
	s_addc_u32 s5, s57, 0
	global_load_lds_dwordx4 v162, s[4:5]

.Lg2_win_loop3:
	s_waitcnt vmcnt(0)
	s_barrier
	s_add_u32 s56, s56, 0x80
	s_addc_u32 s57, s57, 0
	s_add_u32 s58, s58, 0x800
	s_addc_u32 s59, s59, 0
	s_add_u32 m0, s62, 0x8800
	s_add_u32 s4, s56, 0x0
	s_addc_u32 s5, s57, 0
	global_load_lds_dwordx4 v162, s[4:5]
	s_cmp_gt_u32 s70, 1
	s_cbranch_scc1 .Lg2_win_nodma_4
	s_add_u32 m0, s62, 0x9800
	s_add_u32 s4, s56, 0x10000
	s_addc_u32 s5, s57, 0
	global_load_lds_dwordx4 v162, s[4:5]
.Lg2_win_nodma_4:
	global_load_dwordx4 v[200:203], v160, s[58:59] offset:0
	global_load_dwordx4 v[204:207], v160, s[58:59] offset:1024
	global_load_dwordx4 v[208:211], v161, s[58:59] offset:0
	global_load_dwordx4 v[240:243], v161, s[58:59] offset:1024
	ds_read_b128 v[136:139], v156 offset:0
	ds_read_b128 v[140:143], v156 offset:2048
	ds_read_b128 v[144:147], v156 offset:4096
	ds_read_b128 v[164:167], v157 offset:0
	ds_read_b128 v[168:171], v157 offset:2048
	ds_read_b128 v[172:175], v157 offset:4096
	s_waitcnt lgkmcnt(3)
	v_mfma_f32_16x16x32_bf16 v[0:3], v[184:187], v[136:139], v[0:3]
	v_mfma_f32_16x16x32_bf16 v[4:7], v[192:195], v[136:139], v[4:7]
	v_mfma_f32_16x16x32_bf16 v[8:11], v[184:187], v[140:143], v[8:11]
	v_mfma_f32_16x16x32_bf16 v[12:15], v[192:195], v[140:143], v[12:15]
	v_mfma_f32_16x16x32_bf16 v[16:19], v[184:187], v[144:147], v[16:19]
	v_mfma_f32_16x16x32_bf16 v[20:23], v[192:195], v[144:147], v[20:23]
	s_waitcnt lgkmcnt(0)
	v_mfma_f32_16x16x32_bf16 v[0:3], v[188:191], v[164:167], v[0:3]
	v_mfma_f32_16x16x32_bf16 v[4:7], v[196:199], v[164:167], v[4:7]
	v_mfma_f32_16x16x32_bf16 v[8:11], v[188:191], v[168:171], v[8:11]
	v_mfma_f32_16x16x32_bf16 v[12:15], v[196:199], v[168:171], v[12:15]
	v_mfma_f32_16x16x32_bf16 v[16:19], v[188:191], v[172:175], v[16:19]
	v_mfma_f32_16x16x32_bf16 v[20:23], v[196:199], v[172:175], v[20:23]
	s_waitcnt vmcnt(0)
	s_barrier
	s_cmp_ge_u32 s63, 14
	s_cbranch_scc1 .Lg2_win_noissue3
	s_add_u32 s56, s56, 0x80
	s_addc_u32 s57, s57, 0
	s_add_u32 s58, s58, 0x800
	s_addc_u32 s59, s59, 0
	s_add_u32 m0, s62, 0x0
	s_add_u32 s4, s56, 0x0
	s_addc_u32 s5, s57, 0
	global_load_lds_dwordx4 v162, s[4:5]
	s_cmp_gt_u32 s70, 1
	s_cbranch_scc1 .Lg2_win_nodma_5
	s_add_u32 m0, s62, 0x1000
	s_add_u32 s4, s56, 0x10000
	s_addc_u32 s5, s57, 0
	global_load_lds_dwordx4 v162, s[4:5]

.Lg2_win_k2:
	s_add_u32 m0, s62, 0x0
	s_add_u32 s4, s56, 0x0
	s_addc_u32 s5, s57, 0
	global_load_lds_dwordx4 v162, s[4:5]
	global_load_dwordx4 v[184:187], v160, s[58:59] offset:0
	global_load_dwordx4 v[188:191], v160, s[58:59] offset:1024
	global_load_dwordx4 v[192:195], v161, s[58:59] offset:0
	global_load_dwordx4 v[196:199], v161, s[58:59] offset:1024
	v_mov_b32_e32 v0, 0
	v_mov_b32_e32 v1, 0
	v_mov_b32_e32 v2, 0
	v_mov_b32_e32 v3, 0
	v_mov_b32_e32 v4, 0
	v_mov_b32_e32 v5, 0
	v_mov_b32_e32 v6, 0
	v_mov_b32_e32 v7, 0
	v_mov_b32_e32 v8, 0
	v_mov_b32_e32 v9, 0
	v_mov_b32_e32 v10, 0
	v_mov_b32_e32 v11, 0
	v_mov_b32_e32 v12, 0
	v_mov_b32_e32 v13, 0
	v_mov_b32_e32 v14, 0
	v_mov_b32_e32 v15, 0
	s_mov_b32 s63, 0
.Lg2_win_loop2:
	s_waitcnt vmcnt(0)
	s_barrier
	s_add_u32 s56, s56, 0x80
	s_addc_u32 s57, s57, 0
	s_add_u32 s58, s58, 0x800
	s_addc_u32 s59, s59, 0
	s_add_u32 m0, s62, 0x8800
	s_add_u32 s4, s56, 0x0
	s_addc_u32 s5, s57, 0
	global_load_lds_dwordx4 v162, s[4:5]
	global_load_dwordx4 v[200:203], v160, s[58:59] offset:0
	global_load_dwordx4 v[204:207], v160, s[58:59] offset:1024
	global_load_dwordx4 v[208:211], v161, s[58:59] offset:0
	global_load_dwordx4 v[240:243], v161, s[58:59] offset:1024
	ds_read_b128 v[136:139], v156 offset:0
	ds_read_b128 v[140:143], v156 offset:2048
	ds_read_b128 v[164:167], v157 offset:0
	ds_read_b128 v[168:171], v157 offset:2048
	s_waitcnt lgkmcnt(2)
	v_mfma_f32_16x16x32_bf16 v[0:3], v[184:187], v[136:139], v[0:3]
	v_mfma_f32_16x16x32_bf16 v[4:7], v[192:195], v[136:139], v[4:7]
	v_mfma_f32_16x16x32_bf16 v[8:11], v[184:187], v[140:143], v[8:11]
	v_mfma_f32_16x16x32_bf16 v[12:15], v[192:195], v[140:143], v[12:15]
	s_waitcnt lgkmcnt(0)
	v_mfma_f32_16x16x32_bf16 v[0:3], v[188:191], v[164:167], v[0:3]
	v_mfma_f32_16x16x32_bf16 v[4:7], v[196:199], v[164:167], v[4:7]
	v_mfma_f32_16x16x32_bf16 v[8:11], v[188:191], v[168:171], v[8:11]
	v_mfma_f32_16x16x32_bf16 v[12:15], v[196:199], v[168:171], v[12:15]
	s_waitcnt vmcnt(0)
	s_barrier
	s_cmp_ge_u32 s63, 14
	s_cbranch_scc1 .Lg2_win_noissue2
	s_add_u32 s56, s56, 0x80
	s_addc_u32 s57, s57, 0
	s_add_u32 s58, s58, 0x800
	s_addc_u32 s59, s59, 0
	s_add_u32 m0, s62, 0x0
	s_add_u32 s4, s56, 0x0
	s_addc_u32 s5, s57, 0
	global_load_lds_dwordx4 v162, s[4:5]
	global_load_dwordx4 v[184:187], v160, s[58:59] offset:0
	global_load_dwordx4 v[188:191], v160, s[58:59] offset:1024
	global_load_dwordx4 v[192:195], v161, s[58:59] offset:0
	global_load_dwordx4 v[196:199], v161, s[58:59] offset:1024

.Lg2_win_rd_lastaK:
	s_waitcnt lgkmcnt(1)
	global_store_dwordx4 v252, v[0:3], s[60:61]
	s_add_u32 s60, s60, 0x39000
	s_addc_u32 s61, s61, 0
	s_waitcnt lgkmcnt(0)
	global_store_dwordx4 v252, v[4:7], s[60:61]
	s_add_u32 s60, s60, 0x39000
	s_addc_u32 s61, s61, 0
	s_cmp_eq_u32 s65, 0
	s_cbranch_scc1 .Lg2_win_rd_lastK
	s_waitcnt lgkmcnt(0)
	global_store_dwordx4 v252, v[8:11], s[60:61]
	s_add_u32 s60, s60, 0x39000
	s_addc_u32 s61, s61, 0
